# rq tile: 12 register-path loads issued above the loop-top barrier (they only write VGPRs), 4 LDS-DMA loads per wave after it; plus the scanmul move
# baseline (speedup 1.0000x reference)
.LBB0_327:
	v_mov_b32_e32 v130, s67
	v_mov_b32_e32 v131, s66
	v_cndmask_b32_e32 v130, v130, v131, vcc
	v_lshl_add_u32 v168, v130, 7, v155
	v_mov_b32_e32 v153, v161
	v_mov_b32_e32 v192, v181
	v_mov_b32_e32 v190, v183
	v_mov_b32_e32 v191, v182
	v_mov_b32_e32 v166, v157
	v_mov_b32_e32 v130, v186
	v_mov_b32_e32 v131, v187
	v_ashrrev_i32_e32 v169, 31, v168
	v_readfirstlane_b32 s64, v130
	v_readfirstlane_b32 s65, v131
	v_lshlrev_b64 v[130:131], 11, v[168:169]
	v_mov_b32_e32 v167, v189
	v_lshl_add_u64 v[244:245], s[64:65], 0, v[130:131]
	v_lshl_add_u64 v[244:245], v[244:245], 0, v[0:1]
	s_mov_b32 s6, 0xc640000
	s_mov_b32 s7, 0
	v_lshl_add_u64 v[244:245], v[244:245], 0, s[6:7]
	v_and_b32_e32 v247, 0xff, v189
	v_lshrrev_b32_e32 v248, 5, v247
	v_and_b32_e32 v247, 31, v247
	v_add_u32_e32 v249, 32, v248
	v_lshlrev_b32_e32 v249, 11, v249
	v_lshl_add_u32 v242, v247, 4, v249
	v_mov_b32_e32 v243, 0
	v_lshl_add_u64 v[242:243], v[244:245], 0, v[242:243]
	v_lshrrev_b32_e32 v249, 1, v248
	v_add_u32_e32 v249, 16, v249
	v_mul_u32_u24_e32 v249, 0x410, v249
	v_and_b32_e32 v248, 1, v248
	v_lshl_add_u32 v249, v248, 9, v249
	v_lshl_add_u32 v249, v247, 4, v249
	v_add_u32_e32 v246, v149, v249
	s_mov_b32 s6, 0x4000
	global_load_dwordx4 v[130:133], v[242:243], off
	v_lshl_add_u64 v[242:243], v[242:243], 0, s[6:7]
	global_load_dwordx4 v[134:137], v[242:243], off
	v_lshl_add_u64 v[242:243], v[242:243], 0, s[6:7]
	global_load_dwordx4 v[138:141], v[242:243], off
	v_lshl_add_u64 v[242:243], v[242:243], 0, s[6:7]
	global_load_dwordx4 v[142:145], v[242:243], off
	v_lshl_add_u64 v[242:243], v[242:243], 0, s[6:7]
	global_load_dwordx4 v[170:173], v[242:243], off
	v_lshl_add_u64 v[242:243], v[242:243], 0, s[6:7]
	global_load_dwordx4 v[194:197], v[242:243], off
	v_lshl_add_u64 v[242:243], v[242:243], 0, s[6:7]
	global_load_dwordx4 v[218:221], v[242:243], off
	v_lshl_add_u64 v[242:243], v[242:243], 0, s[6:7]
	global_load_dwordx4 v[222:225], v[242:243], off
	v_lshl_add_u64 v[242:243], v[242:243], 0, s[6:7]
	global_load_dwordx4 v[226:229], v[242:243], off
	v_lshl_add_u64 v[242:243], v[242:243], 0, s[6:7]
	global_load_dwordx4 v[230:233], v[242:243], off
	v_lshl_add_u64 v[242:243], v[242:243], 0, s[6:7]
	global_load_dwordx4 v[234:237], v[242:243], off
	v_lshl_add_u64 v[242:243], v[242:243], 0, s[6:7]
	global_load_dwordx4 v[238:241], v[242:243], off
	s_barrier
	v_bfe_u32 v248, v189, 6, 2
	v_lshlrev_b32_e32 v248, 3, v248
	v_bfe_u32 v249, v189, 5, 1
	v_add_u32_e32 v248, v248, v249
	v_lshlrev_b32_e32 v248, 11, v248
	v_and_b32_e32 v249, 31, v189
	v_lshl_add_u32 v248, v249, 4, v248
	v_mov_b32_e32 v249, 0
	v_lshl_add_u64 v[244:245], v[244:245], 0, v[248:249]
	v_readfirstlane_b32 s6, v149
	v_readfirstlane_b32 s7, v189
	s_nop 3
	s_bfe_u32 s7, s7, 0x20006
	s_mul_i32 s7, s7, 0x1040
	s_add_u32 s6, s6, s7
	s_mov_b32 m0, s6
	s_mov_b32 s6, 0x1000
	s_mov_b32 s7, 0
	global_load_lds_dwordx4 v[244:245], off
	s_add_u32 m0, m0, 0x410
	v_lshl_add_u64 v[244:245], v[244:245], 0, s[6:7]
	global_load_lds_dwordx4 v[244:245], off
	s_add_u32 m0, m0, 0x410
	v_lshl_add_u64 v[244:245], v[244:245], 0, s[6:7]
	global_load_lds_dwordx4 v[244:245], off
	s_add_u32 m0, m0, 0x410
	v_lshl_add_u64 v[244:245], v[244:245], 0, s[6:7]
	global_load_lds_dwordx4 v[244:245], off
	s_waitcnt vmcnt(15)
	ds_write2_b64 v246, v[130:131], v[132:133] offset1:1
	s_waitcnt vmcnt(14)
	v_add_u32_e32 v247, 0x1040, v246
	ds_write2_b64 v247, v[134:135], v[136:137] offset1:1
	s_waitcnt vmcnt(13)
	v_add_u32_e32 v247, 0x2080, v246
	ds_write2_b64 v247, v[138:139], v[140:141] offset1:1
	s_waitcnt vmcnt(12)
	v_add_u32_e32 v247, 0x30c0, v246
	ds_write2_b64 v247, v[142:143], v[144:145] offset1:1
	s_waitcnt vmcnt(11)
	v_add_u32_e32 v247, 0x4100, v246
	ds_write2_b64 v247, v[170:171], v[172:173] offset1:1
	s_waitcnt vmcnt(10)
	v_add_u32_e32 v247, 0x5140, v246
	ds_write2_b64 v247, v[194:195], v[196:197] offset1:1
	s_waitcnt vmcnt(9)
	v_add_u32_e32 v247, 0x6180, v246
	ds_write2_b64 v247, v[218:219], v[220:221] offset1:1
	s_waitcnt vmcnt(8)
	v_add_u32_e32 v247, 0x71c0, v246
	ds_write2_b64 v247, v[222:223], v[224:225] offset1:1
	s_waitcnt vmcnt(7)
	v_add_u32_e32 v247, 0x8200, v246
	ds_write2_b64 v247, v[226:227], v[228:229] offset1:1
	s_waitcnt vmcnt(6)
	v_add_u32_e32 v247, 0x9240, v246
	ds_write2_b64 v247, v[230:231], v[232:233] offset1:1
	s_waitcnt vmcnt(5)
	v_add_u32_e32 v247, 0xa280, v246
	ds_write2_b64 v247, v[234:235], v[236:237] offset1:1
	s_waitcnt vmcnt(4)
	v_add_u32_e32 v247, 0xb2c0, v246
	ds_write2_b64 v247, v[238:239], v[240:241] offset1:1
	v_lshl_add_u64 v[210:211], s[64:65], 0, v[162:163]
	s_waitcnt vmcnt(0)
	s_waitcnt lgkmcnt(0)
	s_barrier
	v_ashrrev_i32_e32 v167, 31, v166
	v_lshl_add_u64 v[130:131], v[166:167], 1, v[210:211]
	s_mov_b64 s[6:7], 0x8640000
	v_lshl_add_u64 v[170:171], v[130:131], 0, s[6:7]
	v_add_u32_e32 v250, 0x4000, v178
	ds_read2_b64 v[194:197], v178 offset0:0 offset1:2
	ds_read2_b64 v[218:221], v250 offset0:32 offset1:34
	ds_read2_b64 v[222:225], v178 offset0:4 offset1:6
	ds_read2_b64 v[226:229], v250 offset0:36 offset1:38
	s_nop 0
	v_cvt_pk_bf16_f32 v230, v2, v3
	v_cvt_pk_bf16_f32 v231, v4, v5
	v_cvt_pk_bf16_f32 v232, v6, v7
	v_cvt_pk_bf16_f32 v233, v8, v9
	s_waitcnt lgkmcnt(2)
	s_nop 1
	v_mfma_f32_32x32x16_bf16 v[130:145], v[194:197], v[230:233], 0
	v_mfma_f32_32x32x16_bf16 v[234:249], v[218:221], v[230:233], 0
	ds_read2_b64 v[194:197], v178 offset0:8 offset1:10
	ds_read2_b64 v[218:221], v250 offset0:40 offset1:42
	s_nop 0
	v_cvt_pk_bf16_f32 v230, v10, v11
	v_cvt_pk_bf16_f32 v231, v12, v13
	v_cvt_pk_bf16_f32 v232, v14, v15
	v_cvt_pk_bf16_f32 v233, v16, v17
	s_waitcnt lgkmcnt(2)
	s_nop 1
	v_mfma_f32_32x32x16_bf16 v[130:145], v[222:225], v[230:233], v[130:145]
	v_mfma_f32_32x32x16_bf16 v[234:249], v[226:229], v[230:233], v[234:249]
	ds_read2_b64 v[222:225], v178 offset0:12 offset1:14
	ds_read2_b64 v[226:229], v250 offset0:44 offset1:46
	s_nop 0
	v_cvt_pk_bf16_f32 v230, v18, v19
	v_cvt_pk_bf16_f32 v231, v20, v21
	v_cvt_pk_bf16_f32 v232, v22, v23
	v_cvt_pk_bf16_f32 v233, v24, v25
	s_waitcnt lgkmcnt(2)
	s_nop 1
	v_mfma_f32_32x32x16_bf16 v[130:145], v[194:197], v[230:233], v[130:145]
	v_mfma_f32_32x32x16_bf16 v[234:249], v[218:221], v[230:233], v[234:249]
	ds_read2_b64 v[194:197], v178 offset0:16 offset1:18
	ds_read2_b64 v[218:221], v250 offset0:48 offset1:50
	s_nop 0
	v_cvt_pk_bf16_f32 v230, v26, v27
	v_cvt_pk_bf16_f32 v231, v28, v29
	v_cvt_pk_bf16_f32 v232, v30, v31
	v_cvt_pk_bf16_f32 v233, v32, v33
	s_waitcnt lgkmcnt(2)
	s_nop 1
	v_mfma_f32_32x32x16_bf16 v[130:145], v[222:225], v[230:233], v[130:145]
	v_mfma_f32_32x32x16_bf16 v[234:249], v[226:229], v[230:233], v[234:249]
	ds_read2_b64 v[222:225], v178 offset0:20 offset1:22
	ds_read2_b64 v[226:229], v250 offset0:52 offset1:54
	s_nop 0
	v_cvt_pk_bf16_f32 v230, v34, v35
	v_cvt_pk_bf16_f32 v231, v36, v37
	v_cvt_pk_bf16_f32 v232, v38, v39
	v_cvt_pk_bf16_f32 v233, v40, v41
	s_waitcnt lgkmcnt(2)
	s_nop 1
	v_mfma_f32_32x32x16_bf16 v[130:145], v[194:197], v[230:233], v[130:145]
	v_mfma_f32_32x32x16_bf16 v[234:249], v[218:221], v[230:233], v[234:249]
	ds_read2_b64 v[194:197], v178 offset0:24 offset1:26
	ds_read2_b64 v[218:221], v250 offset0:56 offset1:58
	s_nop 0
	v_cvt_pk_bf16_f32 v230, v42, v43
	v_cvt_pk_bf16_f32 v231, v44, v45
	v_cvt_pk_bf16_f32 v232, v46, v47
	v_cvt_pk_bf16_f32 v233, v48, v49
	s_waitcnt lgkmcnt(2)
	s_nop 1
	v_mfma_f32_32x32x16_bf16 v[130:145], v[222:225], v[230:233], v[130:145]
	v_mfma_f32_32x32x16_bf16 v[234:249], v[226:229], v[230:233], v[234:249]
	ds_read2_b64 v[222:225], v178 offset0:28 offset1:30
	ds_read2_b64 v[226:229], v250 offset0:60 offset1:62
	s_nop 0
	v_cvt_pk_bf16_f32 v230, v50, v51
	v_cvt_pk_bf16_f32 v231, v52, v53
	v_cvt_pk_bf16_f32 v232, v54, v55
	v_cvt_pk_bf16_f32 v233, v56, v57
	s_waitcnt lgkmcnt(2)
	s_nop 1
	v_mfma_f32_32x32x16_bf16 v[130:145], v[194:197], v[230:233], v[130:145]
	v_mfma_f32_32x32x16_bf16 v[234:249], v[218:221], v[230:233], v[234:249]
	ds_read2_b64 v[194:197], v178 offset0:32 offset1:34
	ds_read2_b64 v[218:221], v250 offset0:64 offset1:66
	s_nop 0
	v_cvt_pk_bf16_f32 v230, v58, v59
	v_cvt_pk_bf16_f32 v231, v60, v61
	v_cvt_pk_bf16_f32 v232, v62, v63
	v_cvt_pk_bf16_f32 v233, v64, v65
	s_waitcnt lgkmcnt(2)
	s_nop 1
	v_mfma_f32_32x32x16_bf16 v[130:145], v[222:225], v[230:233], v[130:145]
	v_mfma_f32_32x32x16_bf16 v[234:249], v[226:229], v[230:233], v[234:249]
	ds_read2_b64 v[222:225], v178 offset0:36 offset1:38
	ds_read2_b64 v[226:229], v250 offset0:68 offset1:70
	s_nop 0
	v_cvt_pk_bf16_f32 v230, v66, v67
	v_cvt_pk_bf16_f32 v231, v68, v69
	v_cvt_pk_bf16_f32 v232, v70, v71
	v_cvt_pk_bf16_f32 v233, v72, v73
	s_waitcnt lgkmcnt(2)
	s_nop 1
	v_mfma_f32_32x32x16_bf16 v[130:145], v[194:197], v[230:233], v[130:145]
	v_mfma_f32_32x32x16_bf16 v[234:249], v[218:221], v[230:233], v[234:249]
	ds_read2_b64 v[194:197], v178 offset0:40 offset1:42
	ds_read2_b64 v[218:221], v250 offset0:72 offset1:74
	s_nop 0
	v_cvt_pk_bf16_f32 v230, v74, v75
	v_cvt_pk_bf16_f32 v231, v76, v77
	v_cvt_pk_bf16_f32 v232, v78, v79
	v_cvt_pk_bf16_f32 v233, v80, v81
	s_waitcnt lgkmcnt(2)
	s_nop 1
	v_mfma_f32_32x32x16_bf16 v[130:145], v[222:225], v[230:233], v[130:145]
	v_mfma_f32_32x32x16_bf16 v[234:249], v[226:229], v[230:233], v[234:249]
	ds_read2_b64 v[222:225], v178 offset0:44 offset1:46
	ds_read2_b64 v[226:229], v250 offset0:76 offset1:78
	s_nop 0
	v_cvt_pk_bf16_f32 v230, v82, v83
	v_cvt_pk_bf16_f32 v231, v84, v85
	v_cvt_pk_bf16_f32 v232, v86, v87
	v_cvt_pk_bf16_f32 v233, v88, v89
	s_waitcnt lgkmcnt(2)
	s_nop 1
	v_mfma_f32_32x32x16_bf16 v[130:145], v[194:197], v[230:233], v[130:145]
	v_mfma_f32_32x32x16_bf16 v[234:249], v[218:221], v[230:233], v[234:249]
	ds_read2_b64 v[194:197], v178 offset0:48 offset1:50
	ds_read2_b64 v[218:221], v250 offset0:80 offset1:82
	s_nop 0
	v_cvt_pk_bf16_f32 v230, v90, v91
	v_cvt_pk_bf16_f32 v231, v92, v93
	v_cvt_pk_bf16_f32 v232, v94, v95
	v_cvt_pk_bf16_f32 v233, v96, v97
	s_waitcnt lgkmcnt(2)
	s_nop 1
	v_mfma_f32_32x32x16_bf16 v[130:145], v[222:225], v[230:233], v[130:145]
	v_mfma_f32_32x32x16_bf16 v[234:249], v[226:229], v[230:233], v[234:249]
	ds_read2_b64 v[222:225], v178 offset0:52 offset1:54
	ds_read2_b64 v[226:229], v250 offset0:84 offset1:86
	s_nop 0
	v_cvt_pk_bf16_f32 v230, v98, v99
	v_cvt_pk_bf16_f32 v231, v100, v101
	v_cvt_pk_bf16_f32 v232, v102, v103
	v_cvt_pk_bf16_f32 v233, v104, v105
	s_waitcnt lgkmcnt(2)
	s_nop 1
	v_mfma_f32_32x32x16_bf16 v[130:145], v[194:197], v[230:233], v[130:145]
	v_mfma_f32_32x32x16_bf16 v[234:249], v[218:221], v[230:233], v[234:249]
	ds_read2_b64 v[194:197], v178 offset0:56 offset1:58
	ds_read2_b64 v[218:221], v250 offset0:88 offset1:90
	s_nop 0
	v_cvt_pk_bf16_f32 v230, v106, v107
	v_cvt_pk_bf16_f32 v231, v108, v109
	v_cvt_pk_bf16_f32 v232, v110, v111
	v_cvt_pk_bf16_f32 v233, v112, v113
	s_waitcnt lgkmcnt(2)
	s_nop 1
	v_mfma_f32_32x32x16_bf16 v[130:145], v[222:225], v[230:233], v[130:145]
	v_mfma_f32_32x32x16_bf16 v[234:249], v[226:229], v[230:233], v[234:249]
	ds_read2_b64 v[222:225], v178 offset0:60 offset1:62
	ds_read2_b64 v[226:229], v250 offset0:92 offset1:94
	s_nop 0
	v_cvt_pk_bf16_f32 v230, v114, v115
	v_cvt_pk_bf16_f32 v231, v116, v117
	v_cvt_pk_bf16_f32 v232, v118, v119
	v_cvt_pk_bf16_f32 v233, v120, v121
	s_waitcnt lgkmcnt(2)
	s_nop 1
	v_mfma_f32_32x32x16_bf16 v[130:145], v[194:197], v[230:233], v[130:145]
	v_mfma_f32_32x32x16_bf16 v[234:249], v[218:221], v[230:233], v[234:249]
	s_nop 0
	v_cvt_pk_bf16_f32 v230, v122, v123
	v_cvt_pk_bf16_f32 v231, v124, v125
	v_cvt_pk_bf16_f32 v232, v126, v127
	v_cvt_pk_bf16_f32 v233, v128, v129
	s_waitcnt lgkmcnt(0)
	s_nop 1
	v_mfma_f32_32x32x16_bf16 v[130:145], v[222:225], v[230:233], v[130:145]
	v_mfma_f32_32x32x16_bf16 v[234:249], v[226:229], v[230:233], v[234:249]
	v_or_b32_e32 v172, v168, v174
	v_ashrrev_i32_e32 v173, 31, v172
	v_lshlrev_b64 v[172:173], 12, v[172:173]
	s_mov_b32 s100, 0xaaaaaaaa
	s_mov_b32 s101, 0xaaaaaaaa
	v_and_b32_e32 v220, 1, v189
	v_mul_u32_u24_e32 v220, 0xffe, v220
	v_mov_b32_e32 v221, 0
	v_lshl_add_u64 v[218:219], v[170:171], 0, v[172:173]
	v_lshl_add_u64 v[218:219], v[218:219], 0, v[220:221]
	s_mov_b32 s7, 0
	s_nop 7
	v_fma_f32 v222, 0, v192, v153
	v_add_f32_e32 v223, v153, v192
	v_exp_f32_e32 v222, v222
	v_exp_f32_e32 v223, v223
	s_nop 0
	v_mul_f32_e32 v222, v222, v130
	v_mul_f32_e32 v223, v223, v131
	s_nop 1
	v_mov_b32_dpp v224, v222 quad_perm:[1,0,3,2] row_mask:0xf bank_mask:0xf
	v_mov_b32_dpp v225, v223 quad_perm:[1,0,3,2] row_mask:0xf bank_mask:0xf
	v_cndmask_b32_e64 v226, v222, v225, s[100:101]
	v_cndmask_b32_e64 v227, v224, v223, s[100:101]
	v_cvt_pk_bf16_f32 v226, v226, v227
	s_mov_b32 s6, 0x0
	v_lshl_add_u64 v[228:229], v[218:219], 0, s[6:7]
	global_store_dword v[228:229], v226, off
	v_fma_f32 v222, 2.0, v192, v153
	v_fmamk_f32 v223, v192, 0x40400000, v153
	v_exp_f32_e32 v222, v222
	v_exp_f32_e32 v223, v223
	s_nop 0
	v_mul_f32_e32 v222, v222, v132
	v_mul_f32_e32 v223, v223, v133
	s_nop 1
	v_mov_b32_dpp v224, v222 quad_perm:[1,0,3,2] row_mask:0xf bank_mask:0xf
	v_mov_b32_dpp v225, v223 quad_perm:[1,0,3,2] row_mask:0xf bank_mask:0xf
	v_cndmask_b32_e64 v226, v222, v225, s[100:101]
	v_cndmask_b32_e64 v227, v224, v223, s[100:101]
	v_cvt_pk_bf16_f32 v226, v226, v227
	s_mov_b32 s6, 0x2000
	v_lshl_add_u64 v[228:229], v[218:219], 0, s[6:7]
	global_store_dword v[228:229], v226, off
	v_fmamk_f32 v222, v192, 0x41000000, v153
	v_fmamk_f32 v223, v192, 0x41100000, v153
	v_exp_f32_e32 v222, v222
	v_exp_f32_e32 v223, v223
	s_nop 0
	v_mul_f32_e32 v222, v222, v134
	v_mul_f32_e32 v223, v223, v135
	s_nop 1
	v_mov_b32_dpp v224, v222 quad_perm:[1,0,3,2] row_mask:0xf bank_mask:0xf
	v_mov_b32_dpp v225, v223 quad_perm:[1,0,3,2] row_mask:0xf bank_mask:0xf
	v_cndmask_b32_e64 v226, v222, v225, s[100:101]
	v_cndmask_b32_e64 v227, v224, v223, s[100:101]
	v_cvt_pk_bf16_f32 v226, v226, v227
	s_mov_b32 s6, 0x8000
	v_lshl_add_u64 v[228:229], v[218:219], 0, s[6:7]
	global_store_dword v[228:229], v226, off
	v_fmamk_f32 v222, v192, 0x41200000, v153
	v_fmamk_f32 v223, v192, 0x41300000, v153
	v_exp_f32_e32 v222, v222
	v_exp_f32_e32 v223, v223
	s_nop 0
	v_mul_f32_e32 v222, v222, v136
	v_mul_f32_e32 v223, v223, v137
	s_nop 1
	v_mov_b32_dpp v224, v222 quad_perm:[1,0,3,2] row_mask:0xf bank_mask:0xf
	v_mov_b32_dpp v225, v223 quad_perm:[1,0,3,2] row_mask:0xf bank_mask:0xf
	v_cndmask_b32_e64 v226, v222, v225, s[100:101]
	v_cndmask_b32_e64 v227, v224, v223, s[100:101]
	v_cvt_pk_bf16_f32 v226, v226, v227
	s_mov_b32 s6, 0xa000
	v_lshl_add_u64 v[228:229], v[218:219], 0, s[6:7]
	global_store_dword v[228:229], v226, off
	v_fmamk_f32 v222, v192, 0x41800000, v153
	v_fmamk_f32 v223, v192, 0x41880000, v153
	v_exp_f32_e32 v222, v222
	v_exp_f32_e32 v223, v223
	s_nop 0
	v_mul_f32_e32 v222, v222, v138
	v_mul_f32_e32 v223, v223, v139
	s_nop 1
	v_mov_b32_dpp v224, v222 quad_perm:[1,0,3,2] row_mask:0xf bank_mask:0xf
	v_mov_b32_dpp v225, v223 quad_perm:[1,0,3,2] row_mask:0xf bank_mask:0xf
	v_cndmask_b32_e64 v226, v222, v225, s[100:101]
	v_cndmask_b32_e64 v227, v224, v223, s[100:101]
	v_cvt_pk_bf16_f32 v226, v226, v227
	s_mov_b32 s6, 0x10000
	v_lshl_add_u64 v[228:229], v[218:219], 0, s[6:7]
	global_store_dword v[228:229], v226, off
	v_fmamk_f32 v222, v192, 0x41900000, v153
	v_fmamk_f32 v223, v192, 0x41980000, v153
	v_exp_f32_e32 v222, v222
	v_exp_f32_e32 v223, v223
	s_nop 0
	v_mul_f32_e32 v222, v222, v140
	v_mul_f32_e32 v223, v223, v141
	s_nop 1
	v_mov_b32_dpp v224, v222 quad_perm:[1,0,3,2] row_mask:0xf bank_mask:0xf
	v_mov_b32_dpp v225, v223 quad_perm:[1,0,3,2] row_mask:0xf bank_mask:0xf
	v_cndmask_b32_e64 v226, v222, v225, s[100:101]
	v_cndmask_b32_e64 v227, v224, v223, s[100:101]
	v_cvt_pk_bf16_f32 v226, v226, v227
	s_mov_b32 s6, 0x12000
	v_lshl_add_u64 v[228:229], v[218:219], 0, s[6:7]
	global_store_dword v[228:229], v226, off
	v_fmamk_f32 v222, v192, 0x41c00000, v153
	v_fmamk_f32 v223, v192, 0x41c80000, v153
	v_exp_f32_e32 v222, v222
	v_exp_f32_e32 v223, v223
	s_nop 0
	v_mul_f32_e32 v222, v222, v142
	v_mul_f32_e32 v223, v223, v143
	s_nop 1
	v_mov_b32_dpp v224, v222 quad_perm:[1,0,3,2] row_mask:0xf bank_mask:0xf
	v_mov_b32_dpp v225, v223 quad_perm:[1,0,3,2] row_mask:0xf bank_mask:0xf
	v_cndmask_b32_e64 v226, v222, v225, s[100:101]
	v_cndmask_b32_e64 v227, v224, v223, s[100:101]
	v_cvt_pk_bf16_f32 v226, v226, v227
	s_mov_b32 s6, 0x18000
	v_lshl_add_u64 v[228:229], v[218:219], 0, s[6:7]
	global_store_dword v[228:229], v226, off
	v_fmamk_f32 v222, v192, 0x41d00000, v153
	v_fmamk_f32 v223, v192, 0x41d80000, v153
	v_exp_f32_e32 v222, v222
	v_exp_f32_e32 v223, v223
	s_nop 0
	v_mul_f32_e32 v222, v222, v144
	v_mul_f32_e32 v223, v223, v145
	s_nop 1
	v_mov_b32_dpp v224, v222 quad_perm:[1,0,3,2] row_mask:0xf bank_mask:0xf
	v_mov_b32_dpp v225, v223 quad_perm:[1,0,3,2] row_mask:0xf bank_mask:0xf
	v_cndmask_b32_e64 v226, v222, v225, s[100:101]
	v_cndmask_b32_e64 v227, v224, v223, s[100:101]
	v_cvt_pk_bf16_f32 v226, v226, v227
	s_mov_b32 s6, 0x1a000
	v_lshl_add_u64 v[228:229], v[218:219], 0, s[6:7]
	global_store_dword v[228:229], v226, off
	v_mov_b32_e32 v130, v234
	v_mov_b32_e32 v131, v235
	v_mov_b32_e32 v132, v236
	v_mov_b32_e32 v133, v237
	v_mov_b32_e32 v134, v238
	v_mov_b32_e32 v135, v239
	v_mov_b32_e32 v136, v240
	v_mov_b32_e32 v137, v241
	v_mov_b32_e32 v138, v242
	v_mov_b32_e32 v139, v243
	v_mov_b32_e32 v140, v244
	v_mov_b32_e32 v141, v245
	v_mov_b32_e32 v142, v246
	v_mov_b32_e32 v143, v247
	v_mov_b32_e32 v144, v248
	v_mov_b32_e32 v145, v249
	s_mov_b32 s100, 0xaaaaaaaa
	s_mov_b32 s101, 0xaaaaaaaa
	v_and_b32_e32 v220, 1, v189
	v_mul_u32_u24_e32 v220, 0xffe, v220
	v_mov_b32_e32 v221, 0
	v_lshl_add_u64 v[218:219], v[170:171], 0, v[172:173]
	v_lshl_add_u64 v[218:219], v[218:219], 0, v[220:221]
	s_mov_b32 s7, 0
	s_nop 7
	v_fmamk_f32 v222, v192, 0x42000000, v153
	v_fmamk_f32 v223, v192, 0x42040000, v153
	v_exp_f32_e32 v222, v222
	v_exp_f32_e32 v223, v223
	s_nop 0
	v_mul_f32_e32 v222, v222, v130
	v_mul_f32_e32 v223, v223, v131
	s_nop 1
	v_mov_b32_dpp v224, v222 quad_perm:[1,0,3,2] row_mask:0xf bank_mask:0xf
	v_mov_b32_dpp v225, v223 quad_perm:[1,0,3,2] row_mask:0xf bank_mask:0xf
	v_cndmask_b32_e64 v226, v222, v225, s[100:101]
	v_cndmask_b32_e64 v227, v224, v223, s[100:101]
	v_cvt_pk_bf16_f32 v226, v226, v227
	s_mov_b32 s6, 0x20000
	v_lshl_add_u64 v[228:229], v[218:219], 0, s[6:7]
	global_store_dword v[228:229], v226, off
	v_fmamk_f32 v222, v192, 0x42080000, v153
	v_fmamk_f32 v223, v192, 0x420c0000, v153
	v_exp_f32_e32 v222, v222
	v_exp_f32_e32 v223, v223
	s_nop 0
	v_mul_f32_e32 v222, v222, v132
	v_mul_f32_e32 v223, v223, v133
	s_nop 1
	v_mov_b32_dpp v224, v222 quad_perm:[1,0,3,2] row_mask:0xf bank_mask:0xf
	v_mov_b32_dpp v225, v223 quad_perm:[1,0,3,2] row_mask:0xf bank_mask:0xf
	v_cndmask_b32_e64 v226, v222, v225, s[100:101]
	v_cndmask_b32_e64 v227, v224, v223, s[100:101]
	v_cvt_pk_bf16_f32 v226, v226, v227
	s_mov_b32 s6, 0x22000
	v_lshl_add_u64 v[228:229], v[218:219], 0, s[6:7]
	global_store_dword v[228:229], v226, off
	v_fmamk_f32 v222, v192, 0x42200000, v153
	v_fmamk_f32 v223, v192, 0x42240000, v153
	v_exp_f32_e32 v222, v222
	v_exp_f32_e32 v223, v223
	s_nop 0
	v_mul_f32_e32 v222, v222, v134
	v_mul_f32_e32 v223, v223, v135
	s_nop 1
	v_mov_b32_dpp v224, v222 quad_perm:[1,0,3,2] row_mask:0xf bank_mask:0xf
	v_mov_b32_dpp v225, v223 quad_perm:[1,0,3,2] row_mask:0xf bank_mask:0xf
	v_cndmask_b32_e64 v226, v222, v225, s[100:101]
	v_cndmask_b32_e64 v227, v224, v223, s[100:101]
	v_cvt_pk_bf16_f32 v226, v226, v227
	s_mov_b32 s6, 0x28000
	v_lshl_add_u64 v[228:229], v[218:219], 0, s[6:7]
	global_store_dword v[228:229], v226, off
	v_fmamk_f32 v222, v192, 0x42280000, v153
	v_fmamk_f32 v223, v192, 0x422c0000, v153
	v_exp_f32_e32 v222, v222
	v_exp_f32_e32 v223, v223
	s_nop 0
	v_mul_f32_e32 v222, v222, v136
	v_mul_f32_e32 v223, v223, v137
	s_nop 1
	v_mov_b32_dpp v224, v222 quad_perm:[1,0,3,2] row_mask:0xf bank_mask:0xf
	v_mov_b32_dpp v225, v223 quad_perm:[1,0,3,2] row_mask:0xf bank_mask:0xf
	v_cndmask_b32_e64 v226, v222, v225, s[100:101]
	v_cndmask_b32_e64 v227, v224, v223, s[100:101]
	v_cvt_pk_bf16_f32 v226, v226, v227
	s_mov_b32 s6, 0x2a000
	v_lshl_add_u64 v[228:229], v[218:219], 0, s[6:7]
	global_store_dword v[228:229], v226, off
	v_fmamk_f32 v222, v192, 0x42400000, v153
	v_fmamk_f32 v223, v192, 0x42440000, v153
	v_exp_f32_e32 v222, v222
	v_exp_f32_e32 v223, v223
	s_nop 0
	v_mul_f32_e32 v222, v222, v138
	v_mul_f32_e32 v223, v223, v139
	s_nop 1
	v_mov_b32_dpp v224, v222 quad_perm:[1,0,3,2] row_mask:0xf bank_mask:0xf
	v_mov_b32_dpp v225, v223 quad_perm:[1,0,3,2] row_mask:0xf bank_mask:0xf
	v_cndmask_b32_e64 v226, v222, v225, s[100:101]
	v_cndmask_b32_e64 v227, v224, v223, s[100:101]
	v_cvt_pk_bf16_f32 v226, v226, v227
	s_mov_b32 s6, 0x30000
	v_lshl_add_u64 v[228:229], v[218:219], 0, s[6:7]
	global_store_dword v[228:229], v226, off
	v_fmamk_f32 v222, v192, 0x42480000, v153
	v_fmamk_f32 v223, v192, 0x424c0000, v153
	v_exp_f32_e32 v222, v222
	v_exp_f32_e32 v223, v223
	s_nop 0
	v_mul_f32_e32 v222, v222, v140
	v_mul_f32_e32 v223, v223, v141
	s_nop 1
	v_mov_b32_dpp v224, v222 quad_perm:[1,0,3,2] row_mask:0xf bank_mask:0xf
	v_mov_b32_dpp v225, v223 quad_perm:[1,0,3,2] row_mask:0xf bank_mask:0xf
	v_cndmask_b32_e64 v226, v222, v225, s[100:101]
	v_cndmask_b32_e64 v227, v224, v223, s[100:101]
	v_cvt_pk_bf16_f32 v226, v226, v227
	s_mov_b32 s6, 0x32000
	v_lshl_add_u64 v[228:229], v[218:219], 0, s[6:7]
	global_store_dword v[228:229], v226, off
	v_fmamk_f32 v222, v192, 0x42600000, v153
	v_fmamk_f32 v223, v192, 0x42640000, v153
	v_exp_f32_e32 v222, v222
	v_exp_f32_e32 v223, v223
	s_nop 0
	v_mul_f32_e32 v222, v222, v142
	v_mul_f32_e32 v223, v223, v143
	s_nop 1
	v_mov_b32_dpp v224, v222 quad_perm:[1,0,3,2] row_mask:0xf bank_mask:0xf
	v_mov_b32_dpp v225, v223 quad_perm:[1,0,3,2] row_mask:0xf bank_mask:0xf
	v_cndmask_b32_e64 v226, v222, v225, s[100:101]
	v_cndmask_b32_e64 v227, v224, v223, s[100:101]
	v_cvt_pk_bf16_f32 v226, v226, v227
	s_mov_b32 s6, 0x38000
	v_lshl_add_u64 v[228:229], v[218:219], 0, s[6:7]
	global_store_dword v[228:229], v226, off
	v_fmamk_f32 v222, v192, 0x42680000, v153
	v_fmamk_f32 v223, v192, 0x426c0000, v153
	v_exp_f32_e32 v222, v222
	v_exp_f32_e32 v223, v223
	s_nop 0
	v_mul_f32_e32 v222, v222, v144
	v_mul_f32_e32 v223, v223, v145
	s_nop 1
	v_mov_b32_dpp v224, v222 quad_perm:[1,0,3,2] row_mask:0xf bank_mask:0xf
	v_mov_b32_dpp v225, v223 quad_perm:[1,0,3,2] row_mask:0xf bank_mask:0xf
	v_cndmask_b32_e64 v226, v222, v225, s[100:101]
	v_cndmask_b32_e64 v227, v224, v223, s[100:101]
	v_cvt_pk_bf16_f32 v226, v226, v227
	s_mov_b32 s6, 0x3a000
	v_lshl_add_u64 v[228:229], v[218:219], 0, s[6:7]
	global_store_dword v[228:229], v226, off
	v_add_u32_e32 v250, 0xc000, v178
	v_add_u32_e32 v251, 0x8000, v178
	ds_read2_b64 v[194:197], v251 offset0:64 offset1:66
	ds_read2_b64 v[218:221], v250 offset0:96 offset1:98
	ds_read2_b64 v[222:225], v251 offset0:68 offset1:70
	ds_read2_b64 v[226:229], v250 offset0:100 offset1:102
	s_nop 0
	v_cvt_pk_bf16_f32 v230, v2, v3
	v_cvt_pk_bf16_f32 v231, v4, v5
	v_cvt_pk_bf16_f32 v232, v6, v7
	v_cvt_pk_bf16_f32 v233, v8, v9
	s_waitcnt lgkmcnt(2)
	s_nop 1
	v_mfma_f32_32x32x16_bf16 v[130:145], v[194:197], v[230:233], 0
	v_mfma_f32_32x32x16_bf16 v[234:249], v[218:221], v[230:233], 0
	ds_read2_b64 v[194:197], v251 offset0:72 offset1:74
	ds_read2_b64 v[218:221], v250 offset0:104 offset1:106
	s_nop 0
	v_cvt_pk_bf16_f32 v230, v10, v11
	v_cvt_pk_bf16_f32 v231, v12, v13
	v_cvt_pk_bf16_f32 v232, v14, v15
	v_cvt_pk_bf16_f32 v233, v16, v17
	s_waitcnt lgkmcnt(2)
	s_nop 1
	v_mfma_f32_32x32x16_bf16 v[130:145], v[222:225], v[230:233], v[130:145]
	v_mfma_f32_32x32x16_bf16 v[234:249], v[226:229], v[230:233], v[234:249]
	ds_read2_b64 v[222:225], v251 offset0:76 offset1:78
	ds_read2_b64 v[226:229], v250 offset0:108 offset1:110
	s_nop 0
	v_cvt_pk_bf16_f32 v230, v18, v19
	v_cvt_pk_bf16_f32 v231, v20, v21
	v_cvt_pk_bf16_f32 v232, v22, v23
	v_cvt_pk_bf16_f32 v233, v24, v25
	s_waitcnt lgkmcnt(2)
	s_nop 1
	v_mfma_f32_32x32x16_bf16 v[130:145], v[194:197], v[230:233], v[130:145]
	v_mfma_f32_32x32x16_bf16 v[234:249], v[218:221], v[230:233], v[234:249]
	ds_read2_b64 v[194:197], v251 offset0:80 offset1:82
	ds_read2_b64 v[218:221], v250 offset0:112 offset1:114
	s_nop 0
	v_cvt_pk_bf16_f32 v230, v26, v27
	v_cvt_pk_bf16_f32 v231, v28, v29
	v_cvt_pk_bf16_f32 v232, v30, v31
	v_cvt_pk_bf16_f32 v233, v32, v33
	s_waitcnt lgkmcnt(2)
	s_nop 1
	v_mfma_f32_32x32x16_bf16 v[130:145], v[222:225], v[230:233], v[130:145]
	v_mfma_f32_32x32x16_bf16 v[234:249], v[226:229], v[230:233], v[234:249]
	ds_read2_b64 v[222:225], v251 offset0:84 offset1:86
	ds_read2_b64 v[226:229], v250 offset0:116 offset1:118
	s_nop 0
	v_cvt_pk_bf16_f32 v230, v34, v35
	v_cvt_pk_bf16_f32 v231, v36, v37
	v_cvt_pk_bf16_f32 v232, v38, v39
	v_cvt_pk_bf16_f32 v233, v40, v41
	s_waitcnt lgkmcnt(2)
	s_nop 1
	v_mfma_f32_32x32x16_bf16 v[130:145], v[194:197], v[230:233], v[130:145]
	v_mfma_f32_32x32x16_bf16 v[234:249], v[218:221], v[230:233], v[234:249]
	ds_read2_b64 v[194:197], v251 offset0:88 offset1:90
	ds_read2_b64 v[218:221], v250 offset0:120 offset1:122
	s_nop 0
	v_cvt_pk_bf16_f32 v230, v42, v43
	v_cvt_pk_bf16_f32 v231, v44, v45
	v_cvt_pk_bf16_f32 v232, v46, v47
	v_cvt_pk_bf16_f32 v233, v48, v49
	s_waitcnt lgkmcnt(2)
	s_nop 1
	v_mfma_f32_32x32x16_bf16 v[130:145], v[222:225], v[230:233], v[130:145]
	v_mfma_f32_32x32x16_bf16 v[234:249], v[226:229], v[230:233], v[234:249]
	ds_read2_b64 v[222:225], v251 offset0:92 offset1:94
	ds_read2_b64 v[226:229], v250 offset0:124 offset1:126
	s_nop 0
	v_cvt_pk_bf16_f32 v230, v50, v51
	v_cvt_pk_bf16_f32 v231, v52, v53
	v_cvt_pk_bf16_f32 v232, v54, v55
	v_cvt_pk_bf16_f32 v233, v56, v57
	s_waitcnt lgkmcnt(2)
	s_nop 1
	v_mfma_f32_32x32x16_bf16 v[130:145], v[194:197], v[230:233], v[130:145]
	v_mfma_f32_32x32x16_bf16 v[234:249], v[218:221], v[230:233], v[234:249]
	ds_read2_b64 v[194:197], v251 offset0:96 offset1:98
	ds_read2_b64 v[218:221], v250 offset0:128 offset1:130
	s_nop 0
	v_cvt_pk_bf16_f32 v230, v58, v59
	v_cvt_pk_bf16_f32 v231, v60, v61
	v_cvt_pk_bf16_f32 v232, v62, v63
	v_cvt_pk_bf16_f32 v233, v64, v65
	s_waitcnt lgkmcnt(2)
	s_nop 1
	v_mfma_f32_32x32x16_bf16 v[130:145], v[222:225], v[230:233], v[130:145]
	v_mfma_f32_32x32x16_bf16 v[234:249], v[226:229], v[230:233], v[234:249]
	ds_read2_b64 v[222:225], v251 offset0:100 offset1:102
	ds_read2_b64 v[226:229], v250 offset0:132 offset1:134
	s_nop 0
	v_cvt_pk_bf16_f32 v230, v66, v67
	v_cvt_pk_bf16_f32 v231, v68, v69
	v_cvt_pk_bf16_f32 v232, v70, v71
	v_cvt_pk_bf16_f32 v233, v72, v73
	s_waitcnt lgkmcnt(2)
	s_nop 1
	v_mfma_f32_32x32x16_bf16 v[130:145], v[194:197], v[230:233], v[130:145]
	v_mfma_f32_32x32x16_bf16 v[234:249], v[218:221], v[230:233], v[234:249]
	ds_read2_b64 v[194:197], v251 offset0:104 offset1:106
	ds_read2_b64 v[218:221], v250 offset0:136 offset1:138
	s_nop 0
	v_cvt_pk_bf16_f32 v230, v74, v75
	v_cvt_pk_bf16_f32 v231, v76, v77
	v_cvt_pk_bf16_f32 v232, v78, v79
	v_cvt_pk_bf16_f32 v233, v80, v81
	s_waitcnt lgkmcnt(2)
	s_nop 1
	v_mfma_f32_32x32x16_bf16 v[130:145], v[222:225], v[230:233], v[130:145]
	v_mfma_f32_32x32x16_bf16 v[234:249], v[226:229], v[230:233], v[234:249]
	ds_read2_b64 v[222:225], v251 offset0:108 offset1:110
	ds_read2_b64 v[226:229], v250 offset0:140 offset1:142
	s_nop 0
	v_cvt_pk_bf16_f32 v230, v82, v83
	v_cvt_pk_bf16_f32 v231, v84, v85
	v_cvt_pk_bf16_f32 v232, v86, v87
	v_cvt_pk_bf16_f32 v233, v88, v89
	s_waitcnt lgkmcnt(2)
	s_nop 1
	v_mfma_f32_32x32x16_bf16 v[130:145], v[194:197], v[230:233], v[130:145]
	v_mfma_f32_32x32x16_bf16 v[234:249], v[218:221], v[230:233], v[234:249]
	ds_read2_b64 v[194:197], v251 offset0:112 offset1:114
	ds_read2_b64 v[218:221], v250 offset0:144 offset1:146
	s_nop 0
	v_cvt_pk_bf16_f32 v230, v90, v91
	v_cvt_pk_bf16_f32 v231, v92, v93
	v_cvt_pk_bf16_f32 v232, v94, v95
	v_cvt_pk_bf16_f32 v233, v96, v97
	s_waitcnt lgkmcnt(2)
	s_nop 1
	v_mfma_f32_32x32x16_bf16 v[130:145], v[222:225], v[230:233], v[130:145]
	v_mfma_f32_32x32x16_bf16 v[234:249], v[226:229], v[230:233], v[234:249]
	ds_read2_b64 v[222:225], v251 offset0:116 offset1:118
	ds_read2_b64 v[226:229], v250 offset0:148 offset1:150
	s_nop 0
	v_cvt_pk_bf16_f32 v230, v98, v99
	v_cvt_pk_bf16_f32 v231, v100, v101
	v_cvt_pk_bf16_f32 v232, v102, v103
	v_cvt_pk_bf16_f32 v233, v104, v105
	s_waitcnt lgkmcnt(2)
	s_nop 1
	v_mfma_f32_32x32x16_bf16 v[130:145], v[194:197], v[230:233], v[130:145]
	v_mfma_f32_32x32x16_bf16 v[234:249], v[218:221], v[230:233], v[234:249]
	ds_read2_b64 v[194:197], v251 offset0:120 offset1:122
	ds_read2_b64 v[218:221], v250 offset0:152 offset1:154
	s_nop 0
	v_cvt_pk_bf16_f32 v230, v106, v107
	v_cvt_pk_bf16_f32 v231, v108, v109
	v_cvt_pk_bf16_f32 v232, v110, v111
	v_cvt_pk_bf16_f32 v233, v112, v113
	s_waitcnt lgkmcnt(2)
	s_nop 1
	v_mfma_f32_32x32x16_bf16 v[130:145], v[222:225], v[230:233], v[130:145]
	v_mfma_f32_32x32x16_bf16 v[234:249], v[226:229], v[230:233], v[234:249]
	ds_read2_b64 v[222:225], v251 offset0:124 offset1:126
	ds_read2_b64 v[226:229], v250 offset0:156 offset1:158
	s_nop 0
	v_cvt_pk_bf16_f32 v230, v114, v115
	v_cvt_pk_bf16_f32 v231, v116, v117
	v_cvt_pk_bf16_f32 v232, v118, v119
	v_cvt_pk_bf16_f32 v233, v120, v121
	s_waitcnt lgkmcnt(2)
	s_nop 1
	v_mfma_f32_32x32x16_bf16 v[130:145], v[194:197], v[230:233], v[130:145]
	v_mfma_f32_32x32x16_bf16 v[234:249], v[218:221], v[230:233], v[234:249]
	s_nop 0
	v_cvt_pk_bf16_f32 v230, v122, v123
	v_cvt_pk_bf16_f32 v231, v124, v125
	v_cvt_pk_bf16_f32 v232, v126, v127
	v_cvt_pk_bf16_f32 v233, v128, v129
	s_waitcnt lgkmcnt(0)
	s_nop 1
	v_mfma_f32_32x32x16_bf16 v[130:145], v[222:225], v[230:233], v[130:145]
	v_mfma_f32_32x32x16_bf16 v[234:249], v[226:229], v[230:233], v[234:249]
	s_mov_b32 s100, 0xaaaaaaaa
	s_mov_b32 s101, 0xaaaaaaaa
	v_and_b32_e32 v220, 1, v189
	v_mul_u32_u24_e32 v220, 0xffe, v220
	v_mov_b32_e32 v221, 0
	v_lshl_add_u64 v[218:219], v[170:171], 0, v[172:173]
	v_lshl_add_u64 v[218:219], v[218:219], 0, v[220:221]
	s_mov_b32 s7, 0
	s_nop 7
	v_fmamk_f32 v222, v192, 0x42800000, v153
	v_fmamk_f32 v223, v192, 0x42820000, v153
	v_exp_f32_e32 v222, v222
	v_exp_f32_e32 v223, v223
	s_nop 0
	v_mul_f32_e32 v222, v222, v130
	v_mul_f32_e32 v223, v223, v131
	s_nop 1
	v_mov_b32_dpp v224, v222 quad_perm:[1,0,3,2] row_mask:0xf bank_mask:0xf
	v_mov_b32_dpp v225, v223 quad_perm:[1,0,3,2] row_mask:0xf bank_mask:0xf
	v_cndmask_b32_e64 v226, v222, v225, s[100:101]
	v_cndmask_b32_e64 v227, v224, v223, s[100:101]
	v_cvt_pk_bf16_f32 v226, v226, v227
	s_mov_b32 s6, 0x40000
	v_lshl_add_u64 v[228:229], v[218:219], 0, s[6:7]
	global_store_dword v[228:229], v226, off
	v_fmamk_f32 v222, v192, 0x42840000, v153
	v_fmamk_f32 v223, v192, 0x42860000, v153
	v_exp_f32_e32 v222, v222
	v_exp_f32_e32 v223, v223
	s_nop 0
	v_mul_f32_e32 v222, v222, v132
	v_mul_f32_e32 v223, v223, v133
	s_nop 1
	v_mov_b32_dpp v224, v222 quad_perm:[1,0,3,2] row_mask:0xf bank_mask:0xf
	v_mov_b32_dpp v225, v223 quad_perm:[1,0,3,2] row_mask:0xf bank_mask:0xf
	v_cndmask_b32_e64 v226, v222, v225, s[100:101]
	v_cndmask_b32_e64 v227, v224, v223, s[100:101]
	v_cvt_pk_bf16_f32 v226, v226, v227
	s_mov_b32 s6, 0x42000
	v_lshl_add_u64 v[228:229], v[218:219], 0, s[6:7]
	global_store_dword v[228:229], v226, off
	v_fmamk_f32 v222, v192, 0x42900000, v153
	v_fmamk_f32 v223, v192, 0x42920000, v153
	v_exp_f32_e32 v222, v222
	v_exp_f32_e32 v223, v223
	s_nop 0
	v_mul_f32_e32 v222, v222, v134
	v_mul_f32_e32 v223, v223, v135
	s_nop 1
	v_mov_b32_dpp v224, v222 quad_perm:[1,0,3,2] row_mask:0xf bank_mask:0xf
	v_mov_b32_dpp v225, v223 quad_perm:[1,0,3,2] row_mask:0xf bank_mask:0xf
	v_cndmask_b32_e64 v226, v222, v225, s[100:101]
	v_cndmask_b32_e64 v227, v224, v223, s[100:101]
	v_cvt_pk_bf16_f32 v226, v226, v227
	s_mov_b32 s6, 0x48000
	v_lshl_add_u64 v[228:229], v[218:219], 0, s[6:7]
	global_store_dword v[228:229], v226, off
	v_fmamk_f32 v222, v192, 0x42940000, v153
	v_fmamk_f32 v223, v192, 0x42960000, v153
	v_exp_f32_e32 v222, v222
	v_exp_f32_e32 v223, v223
	s_nop 0
	v_mul_f32_e32 v222, v222, v136
	v_mul_f32_e32 v223, v223, v137
	s_nop 1
	v_mov_b32_dpp v224, v222 quad_perm:[1,0,3,2] row_mask:0xf bank_mask:0xf
	v_mov_b32_dpp v225, v223 quad_perm:[1,0,3,2] row_mask:0xf bank_mask:0xf
	v_cndmask_b32_e64 v226, v222, v225, s[100:101]
	v_cndmask_b32_e64 v227, v224, v223, s[100:101]
	v_cvt_pk_bf16_f32 v226, v226, v227
	s_mov_b32 s6, 0x4a000
	v_lshl_add_u64 v[228:229], v[218:219], 0, s[6:7]
	global_store_dword v[228:229], v226, off
	v_fmamk_f32 v222, v192, 0x42a00000, v153
	v_fmamk_f32 v223, v192, 0x42a20000, v153
	v_exp_f32_e32 v222, v222
	v_exp_f32_e32 v223, v223
	s_nop 0
	v_mul_f32_e32 v222, v222, v138
	v_mul_f32_e32 v223, v223, v139
	s_nop 1
	v_mov_b32_dpp v224, v222 quad_perm:[1,0,3,2] row_mask:0xf bank_mask:0xf
	v_mov_b32_dpp v225, v223 quad_perm:[1,0,3,2] row_mask:0xf bank_mask:0xf
	v_cndmask_b32_e64 v226, v222, v225, s[100:101]
	v_cndmask_b32_e64 v227, v224, v223, s[100:101]
	v_cvt_pk_bf16_f32 v226, v226, v227
	s_mov_b32 s6, 0x50000
	v_lshl_add_u64 v[228:229], v[218:219], 0, s[6:7]
	global_store_dword v[228:229], v226, off
	v_fmamk_f32 v222, v192, 0x42a40000, v153
	v_fmamk_f32 v223, v192, 0x42a60000, v153
	v_exp_f32_e32 v222, v222
	v_exp_f32_e32 v223, v223
	s_nop 0
	v_mul_f32_e32 v222, v222, v140
	v_mul_f32_e32 v223, v223, v141
	s_nop 1
	v_mov_b32_dpp v224, v222 quad_perm:[1,0,3,2] row_mask:0xf bank_mask:0xf
	v_mov_b32_dpp v225, v223 quad_perm:[1,0,3,2] row_mask:0xf bank_mask:0xf
	v_cndmask_b32_e64 v226, v222, v225, s[100:101]
	v_cndmask_b32_e64 v227, v224, v223, s[100:101]
	v_cvt_pk_bf16_f32 v226, v226, v227
	s_mov_b32 s6, 0x52000
	v_lshl_add_u64 v[228:229], v[218:219], 0, s[6:7]
	global_store_dword v[228:229], v226, off
	v_fmamk_f32 v222, v192, 0x42b00000, v153
	v_fmamk_f32 v223, v192, 0x42b20000, v153
	v_exp_f32_e32 v222, v222
	v_exp_f32_e32 v223, v223
	s_nop 0
	v_mul_f32_e32 v222, v222, v142
	v_mul_f32_e32 v223, v223, v143
	s_nop 1
	v_mov_b32_dpp v224, v222 quad_perm:[1,0,3,2] row_mask:0xf bank_mask:0xf
	v_mov_b32_dpp v225, v223 quad_perm:[1,0,3,2] row_mask:0xf bank_mask:0xf
	v_cndmask_b32_e64 v226, v222, v225, s[100:101]
	v_cndmask_b32_e64 v227, v224, v223, s[100:101]
	v_cvt_pk_bf16_f32 v226, v226, v227
	s_mov_b32 s6, 0x58000
	v_lshl_add_u64 v[228:229], v[218:219], 0, s[6:7]
	global_store_dword v[228:229], v226, off
	v_fmamk_f32 v222, v192, 0x42b40000, v153
	v_fmamk_f32 v223, v192, 0x42b60000, v153
	v_exp_f32_e32 v222, v222
	v_exp_f32_e32 v223, v223
	s_nop 0
	v_mul_f32_e32 v222, v222, v144
	v_mul_f32_e32 v223, v223, v145
	s_nop 1
	v_mov_b32_dpp v224, v222 quad_perm:[1,0,3,2] row_mask:0xf bank_mask:0xf
	v_mov_b32_dpp v225, v223 quad_perm:[1,0,3,2] row_mask:0xf bank_mask:0xf
	v_cndmask_b32_e64 v226, v222, v225, s[100:101]
	v_cndmask_b32_e64 v227, v224, v223, s[100:101]
	v_cvt_pk_bf16_f32 v226, v226, v227
	s_mov_b32 s6, 0x5a000
	v_lshl_add_u64 v[228:229], v[218:219], 0, s[6:7]
	global_store_dword v[228:229], v226, off
	v_mov_b32_e32 v130, v234
	v_mov_b32_e32 v131, v235
	v_mov_b32_e32 v132, v236
	v_mov_b32_e32 v133, v237
	v_mov_b32_e32 v134, v238
	v_mov_b32_e32 v135, v239
	v_mov_b32_e32 v136, v240
	v_mov_b32_e32 v137, v241
	v_mov_b32_e32 v138, v242
	v_mov_b32_e32 v139, v243
	v_mov_b32_e32 v140, v244
	v_mov_b32_e32 v141, v245
	v_mov_b32_e32 v142, v246
	v_mov_b32_e32 v143, v247
	v_mov_b32_e32 v144, v248
	v_mov_b32_e32 v145, v249
	s_mov_b32 s100, 0xaaaaaaaa
	s_mov_b32 s101, 0xaaaaaaaa
	v_and_b32_e32 v220, 1, v189
	v_mul_u32_u24_e32 v220, 0xffe, v220
	v_mov_b32_e32 v221, 0
	v_lshl_add_u64 v[218:219], v[170:171], 0, v[172:173]
	v_lshl_add_u64 v[218:219], v[218:219], 0, v[220:221]
	s_mov_b32 s7, 0
	s_nop 7
	v_fmamk_f32 v222, v192, 0x42c00000, v153
	v_fmamk_f32 v223, v192, 0x42c20000, v153
	v_exp_f32_e32 v222, v222
	v_exp_f32_e32 v223, v223
	s_nop 0
	v_mul_f32_e32 v222, v222, v130
	v_mul_f32_e32 v223, v223, v131
	s_nop 1
	v_mov_b32_dpp v224, v222 quad_perm:[1,0,3,2] row_mask:0xf bank_mask:0xf
	v_mov_b32_dpp v225, v223 quad_perm:[1,0,3,2] row_mask:0xf bank_mask:0xf
	v_cndmask_b32_e64 v226, v222, v225, s[100:101]
	v_cndmask_b32_e64 v227, v224, v223, s[100:101]
	v_cvt_pk_bf16_f32 v226, v226, v227
	s_mov_b32 s6, 0x60000
	v_lshl_add_u64 v[228:229], v[218:219], 0, s[6:7]
	global_store_dword v[228:229], v226, off
	v_fmamk_f32 v222, v192, 0x42c40000, v153
	v_fmamk_f32 v223, v192, 0x42c60000, v153
	v_exp_f32_e32 v222, v222
	v_exp_f32_e32 v223, v223
	s_nop 0
	v_mul_f32_e32 v222, v222, v132
	v_mul_f32_e32 v223, v223, v133
	s_nop 1
	v_mov_b32_dpp v224, v222 quad_perm:[1,0,3,2] row_mask:0xf bank_mask:0xf
	v_mov_b32_dpp v225, v223 quad_perm:[1,0,3,2] row_mask:0xf bank_mask:0xf
	v_cndmask_b32_e64 v226, v222, v225, s[100:101]
	v_cndmask_b32_e64 v227, v224, v223, s[100:101]
	v_cvt_pk_bf16_f32 v226, v226, v227
	s_mov_b32 s6, 0x62000
	v_lshl_add_u64 v[228:229], v[218:219], 0, s[6:7]
	global_store_dword v[228:229], v226, off
	v_fmamk_f32 v222, v192, 0x42d00000, v153
	v_fmamk_f32 v223, v192, 0x42d20000, v153
	v_exp_f32_e32 v222, v222
	v_exp_f32_e32 v223, v223
	s_nop 0
	v_mul_f32_e32 v222, v222, v134
	v_mul_f32_e32 v223, v223, v135
	s_nop 1
	v_mov_b32_dpp v224, v222 quad_perm:[1,0,3,2] row_mask:0xf bank_mask:0xf
	v_mov_b32_dpp v225, v223 quad_perm:[1,0,3,2] row_mask:0xf bank_mask:0xf
	v_cndmask_b32_e64 v226, v222, v225, s[100:101]
	v_cndmask_b32_e64 v227, v224, v223, s[100:101]
	v_cvt_pk_bf16_f32 v226, v226, v227
	s_mov_b32 s6, 0x68000
	v_lshl_add_u64 v[228:229], v[218:219], 0, s[6:7]
	global_store_dword v[228:229], v226, off
	v_fmamk_f32 v222, v192, 0x42d40000, v153
	v_fmamk_f32 v223, v192, 0x42d60000, v153
	v_exp_f32_e32 v222, v222
	v_exp_f32_e32 v223, v223
	s_nop 0
	v_mul_f32_e32 v222, v222, v136
	v_mul_f32_e32 v223, v223, v137
	s_nop 1
	v_mov_b32_dpp v224, v222 quad_perm:[1,0,3,2] row_mask:0xf bank_mask:0xf
	v_mov_b32_dpp v225, v223 quad_perm:[1,0,3,2] row_mask:0xf bank_mask:0xf
	v_cndmask_b32_e64 v226, v222, v225, s[100:101]
	v_cndmask_b32_e64 v227, v224, v223, s[100:101]
	v_cvt_pk_bf16_f32 v226, v226, v227
	s_mov_b32 s6, 0x6a000
	v_lshl_add_u64 v[228:229], v[218:219], 0, s[6:7]
	global_store_dword v[228:229], v226, off
	v_fmamk_f32 v222, v192, 0x42e00000, v153
	v_fmamk_f32 v223, v192, 0x42e20000, v153
	v_exp_f32_e32 v222, v222
	v_exp_f32_e32 v223, v223
	s_nop 0
	v_mul_f32_e32 v222, v222, v138
	v_mul_f32_e32 v223, v223, v139
	s_nop 1
	v_mov_b32_dpp v224, v222 quad_perm:[1,0,3,2] row_mask:0xf bank_mask:0xf
	v_mov_b32_dpp v225, v223 quad_perm:[1,0,3,2] row_mask:0xf bank_mask:0xf
	v_cndmask_b32_e64 v226, v222, v225, s[100:101]
	v_cndmask_b32_e64 v227, v224, v223, s[100:101]
	v_cvt_pk_bf16_f32 v226, v226, v227
	s_mov_b32 s6, 0x70000
	v_lshl_add_u64 v[228:229], v[218:219], 0, s[6:7]
	global_store_dword v[228:229], v226, off
	v_fmamk_f32 v222, v192, 0x42e40000, v153
	v_fmamk_f32 v223, v192, 0x42e60000, v153
	v_exp_f32_e32 v222, v222
	v_exp_f32_e32 v223, v223
	s_nop 0
	v_mul_f32_e32 v222, v222, v140
	v_mul_f32_e32 v223, v223, v141
	s_nop 1
	v_mov_b32_dpp v224, v222 quad_perm:[1,0,3,2] row_mask:0xf bank_mask:0xf
	v_mov_b32_dpp v225, v223 quad_perm:[1,0,3,2] row_mask:0xf bank_mask:0xf
	v_cndmask_b32_e64 v226, v222, v225, s[100:101]
	v_cndmask_b32_e64 v227, v224, v223, s[100:101]
	v_cvt_pk_bf16_f32 v226, v226, v227
	s_mov_b32 s6, 0x72000
	v_lshl_add_u64 v[228:229], v[218:219], 0, s[6:7]
	global_store_dword v[228:229], v226, off
	v_fmamk_f32 v222, v192, 0x42f00000, v153
	v_fmamk_f32 v223, v192, 0x42f20000, v153
	v_exp_f32_e32 v222, v222
	v_exp_f32_e32 v223, v223
	s_nop 0
	v_mul_f32_e32 v222, v222, v142
	v_mul_f32_e32 v223, v223, v143
	s_nop 1
	v_mov_b32_dpp v224, v222 quad_perm:[1,0,3,2] row_mask:0xf bank_mask:0xf
	v_mov_b32_dpp v225, v223 quad_perm:[1,0,3,2] row_mask:0xf bank_mask:0xf
	v_cndmask_b32_e64 v226, v222, v225, s[100:101]
	v_cndmask_b32_e64 v227, v224, v223, s[100:101]
	v_cvt_pk_bf16_f32 v226, v226, v227
	s_mov_b32 s6, 0x78000
	v_lshl_add_u64 v[228:229], v[218:219], 0, s[6:7]
	global_store_dword v[228:229], v226, off
	v_fmamk_f32 v222, v192, 0x42f40000, v153
	v_fmamk_f32 v223, v192, 0x42f60000, v153
	v_exp_f32_e32 v222, v222
	v_exp_f32_e32 v223, v223
	s_nop 0
	v_mul_f32_e32 v222, v222, v144
	v_mul_f32_e32 v223, v223, v145
	s_nop 1
	v_mov_b32_dpp v224, v222 quad_perm:[1,0,3,2] row_mask:0xf bank_mask:0xf
	v_mov_b32_dpp v225, v223 quad_perm:[1,0,3,2] row_mask:0xf bank_mask:0xf
	v_cndmask_b32_e64 v226, v222, v225, s[100:101]
	v_cndmask_b32_e64 v227, v224, v223, s[100:101]
	v_cvt_pk_bf16_f32 v226, v226, v227
	s_mov_b32 s6, 0x7a000
	v_lshl_add_u64 v[228:229], v[218:219], 0, s[6:7]
	global_store_dword v[228:229], v226, off
	v_mov_b32_e32 v153, v189
	s_waitcnt vmcnt(63) expcnt(7) lgkmcnt(15)
	s_barrier
	v_lshl_add_u64 v[132:133], s[64:65], 0, v[164:165]
	v_lshlrev_b64 v[130:131], 1, v[168:169]
	v_lshlrev_b64 v[226:227], 14, v[166:167]
	v_lshl_add_u64 v[226:227], s[64:65], 0, v[226:227]
	v_lshl_add_u64 v[226:227], v[226:227], 0, v[130:131]
	v_mov_b32_e32 v228, v152
	v_mov_b32_e32 v229, v1
	v_lshl_add_u64 v[226:227], v[226:227], 0, v[228:229]
	s_mov_b64 s[6:7], 0xf640000
	v_lshl_add_u64 v[226:227], v[226:227], 0, s[6:7]
	global_load_dwordx4 v[234:237], v[226:227], off
	global_load_dwordx4 v[238:241], v[226:227], off offset:32
	global_load_dwordx4 v[242:245], v[226:227], off offset:64
	global_load_dwordx4 v[246:249], v[226:227], off offset:96
	v_lshl_add_u64 v[132:133], v[132:133], 0, v[130:131]
	v_lshlrev_b32_e32 v134, 4, v153
	v_and_b32_e32 v144, 0xf0, v134
	v_mov_b32_e32 v145, v1
	v_lshlrev_b32_e32 v134, 10, v153
	v_lshl_add_u64 v[132:133], v[132:133], 0, v[144:145]
	v_and_b32_e32 v134, 0x3c000, v134
	v_mov_b32_e32 v135, v1
	v_lshl_add_u64 v[172:173], v[132:133], 0, v[134:135]
	s_mov_b32 s6, 0xe640000
	v_add_co_u32_e64 v132, s[6:7], s6, v172
	v_bfe_u32 v145, v153, 4, 4
	s_nop 0
	v_addc_co_u32_e64 v133, s[6:7], 0, v173, s[6:7]
	s_mov_b32 s6, 0xe680000
	s_nop 0
	v_add_co_u32_e64 v136, s[6:7], s6, v172
	global_load_dwordx4 v[132:135], v[132:133], off
	s_nop 0
	v_addc_co_u32_e64 v137, s[6:7], 0, v173, s[6:7]
	s_mov_b32 s6, 0xe6c0000
	s_nop 0
	v_add_co_u32_e64 v140, s[6:7], s6, v172
	global_load_dwordx4 v[136:139], v[136:137], off
	s_nop 0
	v_addc_co_u32_e64 v141, s[6:7], 0, v173, s[6:7]
	s_mov_b32 s6, 0xe700000
	s_nop 0
	v_add_co_u32_e64 v168, s[6:7], s6, v172
	global_load_dwordx4 v[140:143], v[140:141], off
	s_nop 0
	v_addc_co_u32_e64 v169, s[6:7], 0, v173, s[6:7]
	s_mov_b32 s6, 0xe740000
	s_nop 0
	v_add_co_u32_e64 v192, s[6:7], s6, v172
	global_load_dwordx4 v[168:171], v[168:169], off
	s_nop 0
	v_addc_co_u32_e64 v193, s[6:7], 0, v173, s[6:7]
	s_mov_b32 s6, 0xe780000
	s_nop 0
	v_add_co_u32_e64 v196, s[6:7], s6, v172
	global_load_dwordx4 v[192:195], v[192:193], off
	s_nop 0
	v_addc_co_u32_e64 v197, s[6:7], 0, v173, s[6:7]
	s_mov_b32 s6, 0xe7c0000
	s_nop 0
	v_add_co_u32_e64 v208, s[6:7], s6, v172
	global_load_dwordx4 v[196:199], v[196:197], off
	s_nop 0
	v_addc_co_u32_e64 v209, s[6:7], 0, v173, s[6:7]
	s_mov_b32 s6, 0xe800000
	global_load_dwordx4 v[218:221], v[208:209], off
	v_add_co_u32_e64 v208, s[6:7], s6, v172
	v_mul_u32_u24_e32 v145, 0x108, v145
	s_nop 0
	v_addc_co_u32_e64 v209, s[6:7], 0, v173, s[6:7]
	global_load_dwordx4 v[222:225], v[208:209], off
	v_add3_u32 v153, v149, v144, v145
	v_mul_f32 v2, v2, v159
	v_mul_f32 v3, v3, v159
	v_mul_f32 v4, v4, v159
	v_mul_f32 v5, v5, v159
	v_mul_f32 v6, v6, v159
	v_mul_f32 v7, v7, v159
	v_mul_f32 v8, v8, v159
	v_mul_f32 v9, v9, v159
	v_mul_f32 v10, v10, v159
	v_mul_f32 v11, v11, v159
	v_mul_f32 v12, v12, v159
	v_mul_f32 v13, v13, v159
	v_mul_f32 v14, v14, v159
	v_mul_f32 v15, v15, v159
	v_mul_f32 v16, v16, v159
	v_mul_f32 v17, v17, v159
	v_mul_f32 v18, v18, v159
	v_mul_f32 v19, v19, v159
	v_mul_f32 v20, v20, v159
	v_mul_f32 v21, v21, v159
	v_mul_f32 v22, v22, v159
	v_mul_f32 v23, v23, v159
	v_mul_f32 v24, v24, v159
	v_mul_f32 v25, v25, v159
	v_mul_f32 v26, v26, v159
	v_mul_f32 v27, v27, v159
	v_mul_f32 v28, v28, v159
	v_mul_f32 v29, v29, v159
	v_mul_f32 v30, v30, v159
	v_mul_f32 v31, v31, v159
	v_mul_f32 v32, v32, v159
	v_mul_f32 v33, v33, v159
	v_mul_f32 v34, v34, v159
	v_mul_f32 v35, v35, v159
	v_mul_f32 v36, v36, v159
	v_mul_f32 v37, v37, v159
	v_mul_f32 v38, v38, v159
	v_mul_f32 v39, v39, v159
	v_mul_f32 v40, v40, v159
	v_mul_f32 v41, v41, v159
	v_mul_f32 v42, v42, v159
	v_mul_f32 v43, v43, v159
	v_mul_f32 v44, v44, v159
	v_mul_f32 v45, v45, v159
	v_mul_f32 v46, v46, v159
	v_mul_f32 v47, v47, v159
	v_mul_f32 v48, v48, v159
	v_mul_f32 v49, v49, v159
	v_mul_f32 v50, v50, v159
	v_mul_f32 v51, v51, v159
	v_mul_f32 v52, v52, v159
	v_mul_f32 v53, v53, v159
	v_mul_f32 v54, v54, v159
	v_mul_f32 v55, v55, v159
	v_mul_f32 v56, v56, v159
	v_mul_f32 v57, v57, v159
	v_mul_f32 v58, v58, v159
	v_mul_f32 v59, v59, v159
	v_mul_f32 v60, v60, v159
	v_mul_f32 v61, v61, v159
	v_mul_f32 v62, v62, v159
	v_mul_f32 v63, v63, v159
	v_mul_f32 v64, v64, v159
	v_mul_f32 v65, v65, v159
	v_mul_f32 v66, v66, v159
	v_mul_f32 v67, v67, v159
	v_mul_f32 v68, v68, v159
	v_mul_f32 v69, v69, v159
	v_mul_f32 v70, v70, v159
	v_mul_f32 v71, v71, v159
	v_mul_f32 v72, v72, v159
	v_mul_f32 v73, v73, v159
	v_mul_f32 v74, v74, v159
	v_mul_f32 v75, v75, v159
	v_mul_f32 v76, v76, v159
	v_mul_f32 v77, v77, v159
	v_mul_f32 v78, v78, v159
	v_mul_f32 v79, v79, v159
	v_mul_f32 v80, v80, v159
	v_mul_f32 v81, v81, v159
	v_mul_f32 v82, v82, v159
	v_mul_f32 v83, v83, v159
	v_mul_f32 v84, v84, v159
	v_mul_f32 v85, v85, v159
	v_mul_f32 v86, v86, v159
	v_mul_f32 v87, v87, v159
	v_mul_f32 v88, v88, v159
	v_mul_f32 v89, v89, v159
	v_mul_f32 v90, v90, v159
	v_mul_f32 v91, v91, v159
	v_mul_f32 v92, v92, v159
	v_mul_f32 v93, v93, v159
	v_mul_f32 v94, v94, v159
	v_mul_f32 v95, v95, v159
	v_mul_f32 v96, v96, v159
	v_mul_f32 v97, v97, v159
	v_mul_f32 v98, v98, v159
	v_mul_f32 v99, v99, v159
	v_mul_f32 v100, v100, v159
	v_mul_f32 v101, v101, v159
	v_mul_f32 v102, v102, v159
	v_mul_f32 v103, v103, v159
	v_mul_f32 v104, v104, v159
	v_mul_f32 v105, v105, v159
	v_mul_f32 v106, v106, v159
	v_mul_f32 v107, v107, v159
	v_mul_f32 v108, v108, v159
	v_mul_f32 v109, v109, v159
	v_mul_f32 v110, v110, v159
	v_mul_f32 v111, v111, v159
	v_mul_f32 v112, v112, v159
	v_mul_f32 v113, v113, v159
	v_mul_f32 v114, v114, v159
	v_mul_f32 v115, v115, v159
	v_mul_f32 v116, v116, v159
	v_mul_f32 v117, v117, v159
	v_mul_f32 v118, v118, v159
	v_mul_f32 v119, v119, v159
	v_mul_f32 v120, v120, v159
	v_mul_f32 v121, v121, v159
	v_mul_f32 v122, v122, v159
	v_mul_f32 v123, v123, v159
	v_mul_f32 v124, v124, v159
	v_mul_f32 v125, v125, v159
	v_mul_f32 v126, v126, v159
	v_mul_f32 v127, v127, v159
	v_mul_f32 v128, v128, v159
	v_mul_f32 v129, v129, v159
	s_waitcnt vmcnt(7)
	ds_write2_b64 v153, v[132:133], v[134:135] offset1:1
	v_add_u32_e32 v132, 0x1080, v153
	s_waitcnt vmcnt(6)
	ds_write2_b64 v132, v[136:137], v[138:139] offset1:1
	v_add_u32_e32 v132, 0x2100, v153
	s_waitcnt vmcnt(5)
	ds_write2_b64 v132, v[140:141], v[142:143] offset1:1
	v_add_u32_e32 v132, 0x3180, v153
	s_waitcnt vmcnt(4)
	ds_write2_b64 v132, v[168:169], v[170:171] offset1:1
	v_add_u32_e32 v132, 0x4200, v153
	s_waitcnt vmcnt(3)
	ds_write2_b64 v132, v[192:193], v[194:195] offset1:1
	v_add_u32_e32 v132, 0x5280, v153
	s_waitcnt vmcnt(2)
	ds_write2_b64 v132, v[196:197], v[198:199] offset1:1
	v_add_u32_e32 v132, 0x6300, v153
	s_waitcnt vmcnt(1)
	ds_write2_b64 v132, v[218:219], v[220:221] offset1:1
	v_add_u32_e32 v132, 0x7380, v153
	s_waitcnt vmcnt(0)
	ds_write2_b64 v132, v[222:223], v[224:225] offset1:1
	s_mov_b32 s6, 0xe840000
	v_add_co_u32_e64 v132, s[6:7], s6, v172
	s_nop 1
	v_addc_co_u32_e64 v133, s[6:7], 0, v173, s[6:7]
	s_mov_b32 s6, 0xe880000
	s_nop 0
	v_add_co_u32_e64 v136, s[6:7], s6, v172
	global_load_dwordx4 v[132:135], v[132:133], off
	s_nop 0
	v_addc_co_u32_e64 v137, s[6:7], 0, v173, s[6:7]
	s_mov_b32 s6, 0xe8c0000
	s_nop 0
	v_add_co_u32_e64 v140, s[6:7], s6, v172
	global_load_dwordx4 v[136:139], v[136:137], off
	s_nop 0
	v_addc_co_u32_e64 v141, s[6:7], 0, v173, s[6:7]
	s_mov_b32 s6, 0xe900000
	s_nop 0
	v_add_co_u32_e64 v144, s[6:7], s6, v172
	global_load_dwordx4 v[140:143], v[140:141], off
	s_nop 0
	v_addc_co_u32_e64 v145, s[6:7], 0, v173, s[6:7]
	s_mov_b32 s6, 0xe940000
	global_load_dwordx4 v[168:171], v[144:145], off
	v_add_co_u32_e64 v144, s[6:7], s6, v172
	s_nop 1
	v_addc_co_u32_e64 v145, s[6:7], 0, v173, s[6:7]
	s_mov_b32 s6, 0xe980000
	global_load_dwordx4 v[192:195], v[144:145], off
	v_add_co_u32_e64 v144, s[6:7], s6, v172
	s_nop 1
	v_addc_co_u32_e64 v145, s[6:7], 0, v173, s[6:7]
	s_mov_b32 s6, 0xe9c0000
	global_load_dwordx4 v[196:199], v[144:145], off
	v_add_co_u32_e64 v144, s[6:7], s6, v172
	s_nop 1
	v_addc_co_u32_e64 v145, s[6:7], 0, v173, s[6:7]
	s_mov_b32 s6, 0xea00000
	global_load_dwordx4 v[218:221], v[144:145], off
	v_add_co_u32_e64 v144, s[6:7], s6, v172
	s_nop 1
	v_addc_co_u32_e64 v145, s[6:7], 0, v173, s[6:7]
	global_load_dwordx4 v[222:225], v[144:145], off
	v_add_u32_e32 v144, 0x8400, v153
	s_waitcnt vmcnt(7)
	ds_write2_b64 v144, v[132:133], v[134:135] offset1:1
	v_add_u32_e32 v132, 0x9480, v153
	s_waitcnt vmcnt(6)
	ds_write2_b64 v132, v[136:137], v[138:139] offset1:1
	v_add_u32_e32 v132, 0xa500, v153
	s_waitcnt vmcnt(5)
	ds_write2_b64 v132, v[140:141], v[142:143] offset1:1
	v_add_u32_e32 v132, 0xb580, v153
	s_waitcnt vmcnt(4)
	ds_write2_b64 v132, v[168:169], v[170:171] offset1:1
	v_add_u32_e32 v132, 0xc600, v153
	s_waitcnt vmcnt(3)
	ds_write2_b64 v132, v[192:193], v[194:195] offset1:1
	v_add_u32_e32 v132, 0xd680, v153
	s_waitcnt vmcnt(2)
	ds_write2_b64 v132, v[196:197], v[198:199] offset1:1
	v_add_u32_e32 v132, 0xe700, v153
	s_waitcnt vmcnt(1)
	ds_write2_b64 v132, v[218:219], v[220:221] offset1:1
	v_add_u32_e32 v132, 0xf780, v153
	s_waitcnt vmcnt(0)
	ds_write2_b64 v132, v[222:223], v[224:225] offset1:1
	s_waitcnt lgkmcnt(0)
	s_barrier
	v_lshlrev_b64 v[132:133], 14, v[166:167]
	v_lshl_add_u64 v[132:133], s[64:65], 0, v[132:133]
	v_lshl_add_u64 v[130:131], v[132:133], 0, v[130:131]
	v_mov_b32_e32 v153, v1
	v_lshl_add_u64 v[134:135], v[130:131], 0, v[152:153]
	s_mov_b32 s6, 0xf640000
	v_add_co_u32_e64 v130, s[6:7], s6, v134
	s_nop 1
	v_addc_co_u32_e64 v131, s[6:7], 0, v135, s[6:7]
	s_mov_b64 s[6:7], 0xf640000
	v_lshl_add_u64 v[142:143], v[134:135], 0, s[6:7]
	v_mov_b32_e32 v130, v234
	v_mov_b32_e32 v131, v235
	v_mov_b32_e32 v132, v236
	v_mov_b32_e32 v133, v237
	v_mov_b32_e32 v134, v238
	v_mov_b32_e32 v135, v239
	v_mov_b32_e32 v136, v240
	v_mov_b32_e32 v137, v241
	v_mov_b32_e32 v138, v242
	v_mov_b32_e32 v139, v243
	v_mov_b32_e32 v140, v244
	v_mov_b32_e32 v141, v245
	v_mov_b32_e32 v166, v246
	v_mov_b32_e32 v167, v247
	v_mov_b32_e32 v168, v248
	v_mov_b32_e32 v169, v249
	global_load_dwordx4 v[234:237], v[142:143], off offset:128
	global_load_dwordx4 v[238:241], v[142:143], off offset:160
	global_load_dwordx4 v[242:245], v[142:143], off offset:192
	global_load_dwordx4 v[246:249], v[142:143], off offset:224
	v_fma_f32 v144, 0, v191, v190
	v_add_f32_e32 v145, v190, v191
	v_exp_f32_e32 v144, v144
	v_exp_f32_e32 v145, v145
	v_fmamk_f32 v153, v191, 0x42480000, v190
	s_waitcnt vmcnt(4)
	v_lshlrev_b32_e32 v170, 16, v130
	v_and_b32_e32 v171, 0xffff0000, v130
	v_fma_f32 v130, 2.0, v191, v190
	v_pk_mul_f32 v[144:145], v[144:145], v[170:171]
	v_exp_f32_e32 v170, v130
	v_fmamk_f32 v130, v191, 0x40400000, v190
	v_exp_f32_e32 v171, v130
	v_cvt_pk_bf16_f32 v130, v144, v145
	v_lshlrev_b32_e32 v144, 16, v131
	v_and_b32_e32 v145, 0xffff0000, v131
	v_fma_f32 v131, 4.0, v191, v190
	v_pk_mul_f32 v[144:145], v[170:171], v[144:145]
	v_exp_f32_e32 v170, v131
	v_fmamk_f32 v131, v191, 0x40a00000, v190
	v_exp_f32_e32 v171, v131
	v_cvt_pk_bf16_f32 v131, v144, v145
	v_lshlrev_b32_e32 v144, 16, v132
	v_and_b32_e32 v145, 0xffff0000, v132
	v_fmamk_f32 v132, v191, 0x40c00000, v190
	v_pk_mul_f32 v[144:145], v[170:171], v[144:145]
	v_exp_f32_e32 v170, v132
	v_fmamk_f32 v132, v191, 0x40e00000, v190
	v_exp_f32_e32 v171, v132
	v_cvt_pk_bf16_f32 v132, v144, v145
	v_lshlrev_b32_e32 v144, 16, v133
	v_and_b32_e32 v145, 0xffff0000, v133
	v_fmamk_f32 v133, v191, 0x41800000, v190
	v_pk_mul_f32 v[144:145], v[170:171], v[144:145]
	v_exp_f32_e32 v170, v133
	v_fmamk_f32 v133, v191, 0x41880000, v190
	v_exp_f32_e32 v171, v133
	v_cvt_pk_bf16_f32 v133, v144, v145
	s_waitcnt vmcnt(4)
	v_lshlrev_b32_e32 v144, 16, v134
	v_and_b32_e32 v145, 0xffff0000, v134
	v_fmamk_f32 v134, v191, 0x41900000, v190
	v_pk_mul_f32 v[144:145], v[170:171], v[144:145]
	v_exp_f32_e32 v170, v134
	v_fmamk_f32 v134, v191, 0x41980000, v190
	v_exp_f32_e32 v171, v134
	v_cvt_pk_bf16_f32 v134, v144, v145
	v_lshlrev_b32_e32 v144, 16, v135
	v_and_b32_e32 v145, 0xffff0000, v135
	v_fmamk_f32 v135, v191, 0x41a00000, v190
	v_pk_mul_f32 v[144:145], v[170:171], v[144:145]
	v_exp_f32_e32 v170, v135
	v_fmamk_f32 v135, v191, 0x41a80000, v190
	v_exp_f32_e32 v171, v135
	v_cvt_pk_bf16_f32 v135, v144, v145
	v_lshlrev_b32_e32 v144, 16, v136
	v_and_b32_e32 v145, 0xffff0000, v136
	v_fmamk_f32 v136, v191, 0x41b00000, v190
	v_pk_mul_f32 v[144:145], v[170:171], v[144:145]
	v_exp_f32_e32 v170, v136
	v_fmamk_f32 v136, v191, 0x41b80000, v190
	v_exp_f32_e32 v171, v136
	v_cvt_pk_bf16_f32 v136, v144, v145
	v_lshlrev_b32_e32 v144, 16, v137
	v_and_b32_e32 v145, 0xffff0000, v137
	v_fmamk_f32 v137, v191, 0x42000000, v190
	v_pk_mul_f32 v[144:145], v[170:171], v[144:145]
	v_exp_f32_e32 v170, v137
	v_fmamk_f32 v137, v191, 0x42040000, v190
	v_exp_f32_e32 v171, v137
	v_cvt_pk_bf16_f32 v137, v144, v145
	s_waitcnt vmcnt(4)
	v_lshlrev_b32_e32 v144, 16, v138
	v_and_b32_e32 v145, 0xffff0000, v138
	v_fmamk_f32 v138, v191, 0x42080000, v190
	v_pk_mul_f32 v[144:145], v[170:171], v[144:145]
	v_exp_f32_e32 v170, v138
	v_fmamk_f32 v138, v191, 0x420c0000, v190
	v_exp_f32_e32 v171, v138
	v_cvt_pk_bf16_f32 v138, v144, v145
	v_lshlrev_b32_e32 v144, 16, v139
	v_and_b32_e32 v145, 0xffff0000, v139
	v_fmamk_f32 v139, v191, 0x42100000, v190
	v_pk_mul_f32 v[144:145], v[170:171], v[144:145]
	v_exp_f32_e32 v170, v139
	v_fmamk_f32 v139, v191, 0x42140000, v190
	v_exp_f32_e32 v171, v139
	v_cvt_pk_bf16_f32 v139, v144, v145
	v_lshlrev_b32_e32 v144, 16, v140
	v_and_b32_e32 v145, 0xffff0000, v140
	v_fmamk_f32 v140, v191, 0x42180000, v190
	v_pk_mul_f32 v[144:145], v[170:171], v[144:145]
	v_exp_f32_e32 v170, v140
	v_fmamk_f32 v140, v191, 0x421c0000, v190
	v_exp_f32_e32 v171, v140
	v_cvt_pk_bf16_f32 v140, v144, v145
	v_lshlrev_b32_e32 v144, 16, v141
	v_and_b32_e32 v145, 0xffff0000, v141
	v_fmamk_f32 v141, v191, 0x42400000, v190
	v_pk_mul_f32 v[144:145], v[170:171], v[144:145]
	v_exp_f32_e32 v170, v141
	v_fmamk_f32 v141, v191, 0x42440000, v190
	v_exp_f32_e32 v171, v141
	v_cvt_pk_bf16_f32 v141, v144, v145
	s_waitcnt vmcnt(4)
	v_lshlrev_b32_e32 v144, 16, v166
	v_and_b32_e32 v145, 0xffff0000, v166
	v_pk_mul_f32 v[144:145], v[170:171], v[144:145]
	v_exp_f32_e32 v170, v153
	v_fmamk_f32 v153, v191, 0x424c0000, v190
	v_exp_f32_e32 v171, v153
	v_cvt_pk_bf16_f32 v166, v144, v145
	v_lshlrev_b32_e32 v144, 16, v167
	v_and_b32_e32 v145, 0xffff0000, v167
	v_fmamk_f32 v153, v191, 0x42500000, v190
	v_pk_mul_f32 v[144:145], v[170:171], v[144:145]
	v_exp_f32_e32 v170, v153
	v_fmamk_f32 v153, v191, 0x42540000, v190
	v_exp_f32_e32 v171, v153
	v_cvt_pk_bf16_f32 v167, v144, v145
	v_lshlrev_b32_e32 v144, 16, v168
	v_and_b32_e32 v145, 0xffff0000, v168
	v_fmamk_f32 v153, v191, 0x42580000, v190
	v_pk_mul_f32 v[144:145], v[170:171], v[144:145]
	v_exp_f32_e32 v170, v153
	v_fmamk_f32 v153, v191, 0x425c0000, v190
	v_exp_f32_e32 v171, v153
	v_cvt_pk_bf16_f32 v168, v144, v145
	v_lshlrev_b32_e32 v144, 16, v169
	v_and_b32_e32 v145, 0xffff0000, v169
	v_pk_mul_f32 v[144:145], v[170:171], v[144:145]
	s_nop 0
	v_cvt_pk_bf16_f32 v169, v144, v145
	ds_read2_b64 v[170:173], v179 offset1:1
	ds_read2_b64 v[192:195], v179 offset0:4 offset1:5
	ds_read2_b64 v[196:199], v179 offset0:8 offset1:9
	ds_read2_b64 v[218:221], v179 offset0:12 offset1:13
	s_waitcnt lgkmcnt(3)
	v_mfma_f32_32x32x16_bf16 v[2:17], v[170:173], v[130:133], v[2:17]
	v_add_u32_e32 v144, 0x2100, v179
	ds_read2_b64 v[170:173], v144 offset1:1
	s_waitcnt lgkmcnt(3)
	v_mfma_f32_32x32x16_bf16 v[2:17], v[192:195], v[134:137], v[2:17]
	v_add_u32_e32 v144, 0x2120, v179
	ds_read2_b64 v[192:195], v144 offset1:1
	s_waitcnt lgkmcnt(3)
	v_mfma_f32_32x32x16_bf16 v[2:17], v[196:199], v[138:141], v[2:17]
	v_add_u32_e32 v144, 0x2140, v179
	ds_read2_b64 v[196:199], v144 offset1:1
	s_waitcnt lgkmcnt(3)
	v_mfma_f32_32x32x16_bf16 v[2:17], v[218:221], v[166:169], v[2:17]
	v_add_u32_e32 v144, 0x2160, v179
	ds_read2_b64 v[218:221], v144 offset1:1
	s_waitcnt lgkmcnt(3)
	v_mfma_f32_32x32x16_bf16 v[18:33], v[170:173], v[130:133], v[18:33]
	v_add_u32_e32 v144, 0x4200, v179
	ds_read2_b64 v[170:173], v144 offset1:1
	s_waitcnt lgkmcnt(3)
	v_mfma_f32_32x32x16_bf16 v[18:33], v[192:195], v[134:137], v[18:33]
	v_add_u32_e32 v144, 0x4220, v179
	ds_read2_b64 v[192:195], v144 offset1:1
	s_waitcnt lgkmcnt(3)
	v_mfma_f32_32x32x16_bf16 v[18:33], v[196:199], v[138:141], v[18:33]
	v_add_u32_e32 v144, 0x4240, v179
	ds_read2_b64 v[196:199], v144 offset1:1
	s_waitcnt lgkmcnt(3)
	v_mfma_f32_32x32x16_bf16 v[18:33], v[218:221], v[166:169], v[18:33]
	v_add_u32_e32 v144, 0x4260, v179
	ds_read2_b64 v[218:221], v144 offset1:1
	s_waitcnt lgkmcnt(3)
	v_mfma_f32_32x32x16_bf16 v[34:49], v[170:173], v[130:133], v[34:49]
	v_add_u32_e32 v144, 0x6300, v179
	ds_read2_b64 v[170:173], v144 offset1:1
	s_waitcnt lgkmcnt(3)
	v_mfma_f32_32x32x16_bf16 v[34:49], v[192:195], v[134:137], v[34:49]
	v_add_u32_e32 v144, 0x6320, v179
	ds_read2_b64 v[192:195], v144 offset1:1
	s_waitcnt lgkmcnt(3)
	v_mfma_f32_32x32x16_bf16 v[34:49], v[196:199], v[138:141], v[34:49]
	v_add_u32_e32 v144, 0x6340, v179
	ds_read2_b64 v[196:199], v144 offset1:1
	s_waitcnt lgkmcnt(3)
	v_mfma_f32_32x32x16_bf16 v[34:49], v[218:221], v[166:169], v[34:49]
	v_add_u32_e32 v144, 0x6360, v179
	ds_read2_b64 v[218:221], v144 offset1:1
	s_waitcnt lgkmcnt(3)
	v_mfma_f32_32x32x16_bf16 v[50:65], v[170:173], v[130:133], v[50:65]
	v_add_u32_e32 v144, 0x8400, v179
	ds_read2_b64 v[170:173], v144 offset1:1
	s_waitcnt lgkmcnt(3)
	v_mfma_f32_32x32x16_bf16 v[50:65], v[192:195], v[134:137], v[50:65]
	v_add_u32_e32 v144, 0x8420, v179
	ds_read2_b64 v[192:195], v144 offset1:1
	s_waitcnt lgkmcnt(3)
	v_mfma_f32_32x32x16_bf16 v[50:65], v[196:199], v[138:141], v[50:65]
	v_add_u32_e32 v144, 0x8440, v179
	ds_read2_b64 v[196:199], v144 offset1:1
	s_waitcnt lgkmcnt(3)
	v_mfma_f32_32x32x16_bf16 v[50:65], v[218:221], v[166:169], v[50:65]
	v_add_u32_e32 v144, 0x8460, v179
	ds_read2_b64 v[218:221], v144 offset1:1
	s_waitcnt lgkmcnt(3)
	v_mfma_f32_32x32x16_bf16 v[66:81], v[170:173], v[130:133], v[66:81]
	v_add_u32_e32 v144, 0xa500, v179
	ds_read2_b64 v[170:173], v144 offset1:1
	s_waitcnt lgkmcnt(3)
	v_mfma_f32_32x32x16_bf16 v[66:81], v[192:195], v[134:137], v[66:81]
	v_add_u32_e32 v144, 0xa520, v179
	ds_read2_b64 v[192:195], v144 offset1:1
	s_waitcnt lgkmcnt(3)
	v_mfma_f32_32x32x16_bf16 v[66:81], v[196:199], v[138:141], v[66:81]
	v_add_u32_e32 v144, 0xa540, v179
	ds_read2_b64 v[196:199], v144 offset1:1
	s_waitcnt lgkmcnt(3)
	v_mfma_f32_32x32x16_bf16 v[66:81], v[218:221], v[166:169], v[66:81]
	v_add_u32_e32 v144, 0xa560, v179
	ds_read2_b64 v[218:221], v144 offset1:1
	s_waitcnt lgkmcnt(3)
	v_mfma_f32_32x32x16_bf16 v[82:97], v[170:173], v[130:133], v[82:97]
	v_add_u32_e32 v144, 0xc600, v179
	ds_read2_b64 v[170:173], v144 offset1:1
	s_waitcnt lgkmcnt(3)
	v_mfma_f32_32x32x16_bf16 v[82:97], v[192:195], v[134:137], v[82:97]
	v_add_u32_e32 v144, 0xc620, v179
	ds_read2_b64 v[192:195], v144 offset1:1
	s_waitcnt lgkmcnt(3)
	v_mfma_f32_32x32x16_bf16 v[82:97], v[196:199], v[138:141], v[82:97]
	v_add_u32_e32 v144, 0xc640, v179
	ds_read2_b64 v[196:199], v144 offset1:1
	s_waitcnt lgkmcnt(3)
	v_mfma_f32_32x32x16_bf16 v[82:97], v[218:221], v[166:169], v[82:97]
	v_add_u32_e32 v144, 0xc660, v179
	ds_read2_b64 v[218:221], v144 offset1:1
	s_waitcnt lgkmcnt(3)
	v_mfma_f32_32x32x16_bf16 v[98:113], v[170:173], v[130:133], v[98:113]
	v_add_u32_e32 v144, 0xe700, v179
	ds_read2_b64 v[170:173], v144 offset1:1
	s_waitcnt lgkmcnt(3)
	v_mfma_f32_32x32x16_bf16 v[98:113], v[192:195], v[134:137], v[98:113]
	v_add_u32_e32 v144, 0xe720, v179
	ds_read2_b64 v[192:195], v144 offset1:1
	s_waitcnt lgkmcnt(3)
	v_mfma_f32_32x32x16_bf16 v[98:113], v[196:199], v[138:141], v[98:113]
	v_add_u32_e32 v144, 0xe740, v179
	ds_read2_b64 v[196:199], v144 offset1:1
	s_waitcnt lgkmcnt(3)
	v_mfma_f32_32x32x16_bf16 v[98:113], v[218:221], v[166:169], v[98:113]
	v_add_u32_e32 v144, 0xe760, v179
	ds_read2_b64 v[218:221], v144 offset1:1
	s_waitcnt lgkmcnt(3)
	v_mfma_f32_32x32x16_bf16 v[114:129], v[170:173], v[130:133], v[114:129]
	s_waitcnt lgkmcnt(2)
	v_mfma_f32_32x32x16_bf16 v[114:129], v[192:195], v[134:137], v[114:129]
	s_waitcnt lgkmcnt(1)
	v_mfma_f32_32x32x16_bf16 v[114:129], v[196:199], v[138:141], v[114:129]
	s_waitcnt lgkmcnt(0)
	v_mfma_f32_32x32x16_bf16 v[114:129], v[218:221], v[166:169], v[114:129]
	v_fmamk_f32 v134, v191, 0x42800000, v190
	v_fmamk_f32 v135, v191, 0x42820000, v190
	v_exp_f32_e32 v134, v134
	v_exp_f32_e32 v135, v135
	v_fmamk_f32 v138, v191, 0x42a00000, v190
	v_fmamk_f32 v139, v191, 0x42a20000, v190
	v_exp_f32_e32 v138, v138
	v_exp_f32_e32 v139, v139
	v_fmamk_f32 v144, v191, 0x42c00000, v190
	v_fmamk_f32 v145, v191, 0x42c20000, v190
	v_exp_f32_e32 v144, v144
	v_exp_f32_e32 v145, v145
	v_fmamk_f32 v153, v191, 0x42e00000, v190
	s_waitcnt vmcnt(0)
	v_mov_b32_e32 v130, v234
	v_mov_b32_e32 v131, v235
	v_mov_b32_e32 v132, v236
	v_mov_b32_e32 v133, v237
	v_lshlrev_b32_e32 v136, 16, v130
	v_and_b32_e32 v137, 0xffff0000, v130
	v_pk_mul_f32 v[134:135], v[134:135], v[136:137]
	v_lshlrev_b32_e32 v136, 16, v131
	v_cvt_pk_bf16_f32 v130, v134, v135
	v_fmamk_f32 v134, v191, 0x42840000, v190
	v_fmamk_f32 v135, v191, 0x42860000, v190
	v_exp_f32_e32 v134, v134
	v_exp_f32_e32 v135, v135
	v_and_b32_e32 v137, 0xffff0000, v131
	v_pk_mul_f32 v[134:135], v[134:135], v[136:137]
	s_nop 0
	v_cvt_pk_bf16_f32 v131, v134, v135
	v_fmamk_f32 v134, v191, 0x42880000, v190
	v_fmamk_f32 v135, v191, 0x428a0000, v190
	v_exp_f32_e32 v134, v134
	v_exp_f32_e32 v135, v135
	v_lshlrev_b32_e32 v136, 16, v132
	v_and_b32_e32 v137, 0xffff0000, v132
	v_pk_mul_f32 v[134:135], v[134:135], v[136:137]
	s_nop 0
	v_cvt_pk_bf16_f32 v132, v134, v135
	v_fmamk_f32 v134, v191, 0x428c0000, v190
	v_fmamk_f32 v135, v191, 0x428e0000, v190
	v_exp_f32_e32 v134, v134
	v_exp_f32_e32 v135, v135
	v_lshlrev_b32_e32 v136, 16, v133
	v_and_b32_e32 v137, 0xffff0000, v133
	v_pk_mul_f32 v[134:135], v[134:135], v[136:137]
	s_nop 0
	v_cvt_pk_bf16_f32 v133, v134, v135
	s_waitcnt vmcnt(0)
	v_mov_b32_e32 v134, v238
	v_mov_b32_e32 v135, v239
	v_mov_b32_e32 v136, v240
	v_mov_b32_e32 v137, v241
	v_lshlrev_b32_e32 v140, 16, v134
	v_and_b32_e32 v141, 0xffff0000, v134
	v_pk_mul_f32 v[138:139], v[138:139], v[140:141]
	v_lshlrev_b32_e32 v140, 16, v135
	v_cvt_pk_bf16_f32 v134, v138, v139
	v_fmamk_f32 v138, v191, 0x42a40000, v190
	v_fmamk_f32 v139, v191, 0x42a60000, v190
	v_exp_f32_e32 v138, v138
	v_exp_f32_e32 v139, v139
	v_and_b32_e32 v141, 0xffff0000, v135
	v_pk_mul_f32 v[138:139], v[138:139], v[140:141]
	s_nop 0
	v_cvt_pk_bf16_f32 v135, v138, v139
	v_fmamk_f32 v138, v191, 0x42a80000, v190
	v_fmamk_f32 v139, v191, 0x42aa0000, v190
	v_exp_f32_e32 v138, v138
	v_exp_f32_e32 v139, v139
	v_lshlrev_b32_e32 v140, 16, v136
	v_and_b32_e32 v141, 0xffff0000, v136
	v_pk_mul_f32 v[138:139], v[138:139], v[140:141]
	s_nop 0
	v_cvt_pk_bf16_f32 v136, v138, v139
	v_fmamk_f32 v138, v191, 0x42ac0000, v190
	v_fmamk_f32 v139, v191, 0x42ae0000, v190
	v_exp_f32_e32 v138, v138
	v_exp_f32_e32 v139, v139
	v_lshlrev_b32_e32 v140, 16, v137
	v_and_b32_e32 v141, 0xffff0000, v137
	v_pk_mul_f32 v[138:139], v[138:139], v[140:141]
	s_nop 0
	v_cvt_pk_bf16_f32 v137, v138, v139
	s_waitcnt vmcnt(0)
	v_mov_b32_e32 v138, v242
	v_mov_b32_e32 v139, v243
	v_mov_b32_e32 v140, v244
	v_mov_b32_e32 v141, v245
	v_lshlrev_b32_e32 v166, 16, v138
	v_and_b32_e32 v167, 0xffff0000, v138
	v_pk_mul_f32 v[144:145], v[144:145], v[166:167]
	v_lshlrev_b32_e32 v166, 16, v139
	v_cvt_pk_bf16_f32 v138, v144, v145
	v_fmamk_f32 v144, v191, 0x42c40000, v190
	v_fmamk_f32 v145, v191, 0x42c60000, v190
	v_exp_f32_e32 v144, v144
	v_exp_f32_e32 v145, v145
	v_and_b32_e32 v167, 0xffff0000, v139
	v_pk_mul_f32 v[144:145], v[144:145], v[166:167]
	s_nop 0
	v_cvt_pk_bf16_f32 v139, v144, v145
	v_fmamk_f32 v144, v191, 0x42c80000, v190
	v_fmamk_f32 v145, v191, 0x42ca0000, v190
	v_exp_f32_e32 v144, v144
	v_exp_f32_e32 v145, v145
	v_lshlrev_b32_e32 v166, 16, v140
	v_and_b32_e32 v167, 0xffff0000, v140
	v_pk_mul_f32 v[144:145], v[144:145], v[166:167]
	s_nop 0
	v_cvt_pk_bf16_f32 v140, v144, v145
	v_fmamk_f32 v144, v191, 0x42cc0000, v190
	v_fmamk_f32 v145, v191, 0x42ce0000, v190
	v_exp_f32_e32 v144, v144
	v_exp_f32_e32 v145, v145
	v_lshlrev_b32_e32 v166, 16, v141
	v_and_b32_e32 v167, 0xffff0000, v141
	v_pk_mul_f32 v[144:145], v[144:145], v[166:167]
	s_nop 0
	v_cvt_pk_bf16_f32 v141, v144, v145
	v_exp_f32_e32 v166, v153
	v_fmamk_f32 v153, v191, 0x42e20000, v190
	v_exp_f32_e32 v167, v153
	v_fmamk_f32 v153, v191, 0x42e40000, v190
	s_waitcnt vmcnt(0)
	v_mov_b32_e32 v142, v246
	v_mov_b32_e32 v143, v247
	v_mov_b32_e32 v144, v248
	v_mov_b32_e32 v145, v249
	v_lshlrev_b32_e32 v168, 16, v142
	v_and_b32_e32 v169, 0xffff0000, v142
	v_pk_mul_f32 v[166:167], v[166:167], v[168:169]
	v_lshlrev_b32_e32 v168, 16, v143
	v_cvt_pk_bf16_f32 v142, v166, v167
	v_exp_f32_e32 v166, v153
	v_fmamk_f32 v153, v191, 0x42e60000, v190
	v_exp_f32_e32 v167, v153
	v_and_b32_e32 v169, 0xffff0000, v143
	v_fmamk_f32 v153, v191, 0x42e80000, v190
	v_pk_mul_f32 v[166:167], v[166:167], v[168:169]
	s_nop 0
	v_cvt_pk_bf16_f32 v143, v166, v167
	v_exp_f32_e32 v166, v153
	v_fmamk_f32 v153, v191, 0x42ea0000, v190
	v_exp_f32_e32 v167, v153
	v_lshlrev_b32_e32 v168, 16, v144
	v_and_b32_e32 v169, 0xffff0000, v144
	v_fmamk_f32 v153, v191, 0x42ec0000, v190
	v_pk_mul_f32 v[166:167], v[166:167], v[168:169]
	v_fmac_f32_e32 v190, 0x42ee0000, v191
	v_cvt_pk_bf16_f32 v144, v166, v167
	v_exp_f32_e32 v166, v153
	v_exp_f32_e32 v167, v190
	v_lshlrev_b32_e32 v168, 16, v145
	v_and_b32_e32 v169, 0xffff0000, v145
	v_pk_mul_f32 v[166:167], v[166:167], v[168:169]
	s_nop 0
	v_cvt_pk_bf16_f32 v145, v166, v167
	ds_read2_b64 v[166:169], v179 offset0:16 offset1:17
	ds_read2_b64 v[170:173], v179 offset0:20 offset1:21
	ds_read2_b64 v[190:193], v179 offset0:24 offset1:25
	ds_read2_b64 v[194:197], v179 offset0:28 offset1:29
	s_waitcnt lgkmcnt(3)
	v_mfma_f32_32x32x16_bf16 v[2:17], v[166:169], v[130:133], v[2:17]
	v_add_u32_e32 v153, 0x2180, v179
	ds_read2_b64 v[166:169], v153 offset1:1
	s_waitcnt lgkmcnt(3)
	v_mfma_f32_32x32x16_bf16 v[2:17], v[170:173], v[134:137], v[2:17]
	v_add_u32_e32 v153, 0x21a0, v179
	ds_read2_b64 v[170:173], v153 offset1:1
	s_waitcnt lgkmcnt(3)
	v_mfma_f32_32x32x16_bf16 v[2:17], v[190:193], v[138:141], v[2:17]
	v_add_u32_e32 v153, 0x21c0, v179
	ds_read2_b64 v[190:193], v153 offset1:1
	s_waitcnt lgkmcnt(3)
	v_mfma_f32_32x32x16_bf16 v[2:17], v[194:197], v[142:145], v[2:17]
	v_add_u32_e32 v153, 0x21e0, v179
	ds_read2_b64 v[194:197], v153 offset1:1
	s_waitcnt lgkmcnt(3)
	v_mfma_f32_32x32x16_bf16 v[18:33], v[166:169], v[130:133], v[18:33]
	v_add_u32_e32 v153, 0x4280, v179
	ds_read2_b64 v[166:169], v153 offset1:1
	s_waitcnt lgkmcnt(3)
	v_mfma_f32_32x32x16_bf16 v[18:33], v[170:173], v[134:137], v[18:33]
	v_add_u32_e32 v153, 0x42a0, v179
	ds_read2_b64 v[170:173], v153 offset1:1
	s_waitcnt lgkmcnt(3)
	v_mfma_f32_32x32x16_bf16 v[18:33], v[190:193], v[138:141], v[18:33]
	v_add_u32_e32 v153, 0x42c0, v179
	ds_read2_b64 v[190:193], v153 offset1:1
	s_waitcnt lgkmcnt(3)
	v_mfma_f32_32x32x16_bf16 v[18:33], v[194:197], v[142:145], v[18:33]
	v_add_u32_e32 v153, 0x42e0, v179
	ds_read2_b64 v[194:197], v153 offset1:1
	s_waitcnt lgkmcnt(3)
	v_mfma_f32_32x32x16_bf16 v[34:49], v[166:169], v[130:133], v[34:49]
	v_add_u32_e32 v153, 0x6380, v179
	ds_read2_b64 v[166:169], v153 offset1:1
	s_waitcnt lgkmcnt(3)
	v_mfma_f32_32x32x16_bf16 v[34:49], v[170:173], v[134:137], v[34:49]
	v_add_u32_e32 v153, 0x63a0, v179
	ds_read2_b64 v[170:173], v153 offset1:1
	s_waitcnt lgkmcnt(3)
	v_mfma_f32_32x32x16_bf16 v[34:49], v[190:193], v[138:141], v[34:49]
	v_add_u32_e32 v153, 0x63c0, v179
	ds_read2_b64 v[190:193], v153 offset1:1
	s_waitcnt lgkmcnt(3)
	v_mfma_f32_32x32x16_bf16 v[34:49], v[194:197], v[142:145], v[34:49]
	v_add_u32_e32 v153, 0x63e0, v179
	ds_read2_b64 v[194:197], v153 offset1:1
	s_waitcnt lgkmcnt(3)
	v_mfma_f32_32x32x16_bf16 v[50:65], v[166:169], v[130:133], v[50:65]
	v_add_u32_e32 v153, 0x8480, v179
	ds_read2_b64 v[166:169], v153 offset1:1
	s_waitcnt lgkmcnt(3)
	v_mfma_f32_32x32x16_bf16 v[50:65], v[170:173], v[134:137], v[50:65]
	v_add_u32_e32 v153, 0x84a0, v179
	ds_read2_b64 v[170:173], v153 offset1:1
	s_waitcnt lgkmcnt(3)
	v_mfma_f32_32x32x16_bf16 v[50:65], v[190:193], v[138:141], v[50:65]
	v_add_u32_e32 v153, 0x84c0, v179
	ds_read2_b64 v[190:193], v153 offset1:1
	s_waitcnt lgkmcnt(3)
	v_mfma_f32_32x32x16_bf16 v[50:65], v[194:197], v[142:145], v[50:65]
	v_add_u32_e32 v153, 0x84e0, v179
	ds_read2_b64 v[194:197], v153 offset1:1
	s_waitcnt lgkmcnt(3)
	v_mfma_f32_32x32x16_bf16 v[66:81], v[166:169], v[130:133], v[66:81]
	v_add_u32_e32 v153, 0xa580, v179
	ds_read2_b64 v[166:169], v153 offset1:1
	s_waitcnt lgkmcnt(3)
	v_mfma_f32_32x32x16_bf16 v[66:81], v[170:173], v[134:137], v[66:81]
	v_add_u32_e32 v153, 0xa5a0, v179
	ds_read2_b64 v[170:173], v153 offset1:1
	s_waitcnt lgkmcnt(3)
	v_mfma_f32_32x32x16_bf16 v[66:81], v[190:193], v[138:141], v[66:81]
	v_add_u32_e32 v153, 0xa5c0, v179
	ds_read2_b64 v[190:193], v153 offset1:1
	s_waitcnt lgkmcnt(3)
	v_mfma_f32_32x32x16_bf16 v[66:81], v[194:197], v[142:145], v[66:81]
	v_add_u32_e32 v153, 0xa5e0, v179
	ds_read2_b64 v[194:197], v153 offset1:1
	s_waitcnt lgkmcnt(3)
	v_mfma_f32_32x32x16_bf16 v[82:97], v[166:169], v[130:133], v[82:97]
	v_add_u32_e32 v153, 0xc680, v179
	ds_read2_b64 v[166:169], v153 offset1:1
	s_waitcnt lgkmcnt(3)
	v_mfma_f32_32x32x16_bf16 v[82:97], v[170:173], v[134:137], v[82:97]
	v_add_u32_e32 v153, 0xc6a0, v179
	ds_read2_b64 v[170:173], v153 offset1:1
	s_waitcnt lgkmcnt(3)
	v_mfma_f32_32x32x16_bf16 v[82:97], v[190:193], v[138:141], v[82:97]
	v_add_u32_e32 v153, 0xc6c0, v179
	ds_read2_b64 v[190:193], v153 offset1:1
	s_waitcnt lgkmcnt(3)
	v_mfma_f32_32x32x16_bf16 v[82:97], v[194:197], v[142:145], v[82:97]
	v_add_u32_e32 v153, 0xc6e0, v179
	ds_read2_b64 v[194:197], v153 offset1:1
	s_waitcnt lgkmcnt(3)
	v_mfma_f32_32x32x16_bf16 v[98:113], v[166:169], v[130:133], v[98:113]
	v_add_u32_e32 v153, 0xe780, v179
	ds_read2_b64 v[166:169], v153 offset1:1
	s_waitcnt lgkmcnt(3)
	v_mfma_f32_32x32x16_bf16 v[98:113], v[170:173], v[134:137], v[98:113]
	v_add_u32_e32 v153, 0xe7a0, v179
	ds_read2_b64 v[170:173], v153 offset1:1
	s_waitcnt lgkmcnt(3)
	v_mfma_f32_32x32x16_bf16 v[98:113], v[190:193], v[138:141], v[98:113]
	v_add_u32_e32 v153, 0xe7c0, v179
	ds_read2_b64 v[190:193], v153 offset1:1
	s_waitcnt lgkmcnt(3)
	v_mfma_f32_32x32x16_bf16 v[98:113], v[194:197], v[142:145], v[98:113]
	v_add_u32_e32 v153, 0xe7e0, v179
	ds_read2_b64 v[194:197], v153 offset1:1
	s_waitcnt lgkmcnt(3)
	v_mfma_f32_32x32x16_bf16 v[114:129], v[166:169], v[130:133], v[114:129]
	s_waitcnt lgkmcnt(2)
	v_mfma_f32_32x32x16_bf16 v[114:129], v[170:173], v[134:137], v[114:129]
	s_waitcnt lgkmcnt(1)
	v_mfma_f32_32x32x16_bf16 v[114:129], v[190:193], v[138:141], v[114:129]
	s_waitcnt lgkmcnt(0)
	v_mfma_f32_32x32x16_bf16 v[114:129], v[194:197], v[142:145], v[114:129]
	s_add_i32 s66, s66, 1
	s_add_i32 s67, s67, -1
	s_cmp_eq_u32 s67, -1
	s_cbranch_scc0 .LBB0_327
	s_and_b64 vcc, exec, s[4:5]
	s_mov_b64 s[4:5], -1
	s_cbranch_vccnz .LBB0_330
	s_mov_b64 s[4:5], 0
